# C1 with one static s_setprio 1 for waves 4-7 per GEMM tile and all per-segment priority flips removed
# baseline (speedup 1.0000x reference)
; #define PG8_STAGE(bufoff, gbase, voff) do { _Pragma("unroll") for (int _i = 0; _i < 2; ++_i) \
;         __builtin_amdgcn_global_load_lds((const unsigned*)((const char*)(gbase) + (voff)[_i]), (PG8_LAS unsigned*)(lds + (bufoff) + ldsw + _i * 8192), 16, 0, 0); } while (0)
; #define PG8_LDA(dst, b, h) do { _Pragma("unroll") for (int m = 0; m < 4; ++m) _Pragma("unroll") for (int k = 0; k < 2; ++k) dst[m][k] = *(const PG8_LAS bf16x8*)(lds + PG8_SA(b, h) + aoff + m * 2048 + k * 1024); } while (0)
; #define PG8_LDB(dst, b, h) do { _Pragma("unroll") for (int n = 0; n < 2; ++n) _Pragma("unroll") for (int k = 0; k < 2; ++k) dst[n][k] = *(const PG8_LAS bf16x8*)(lds + PG8_SB(b, h) + boff + n * 2048 + k * 1024); } while (0)
; #define PG8_WAIT_V(n) asm volatile("s_waitcnt vmcnt(" #n ")" ::: "memory")
; #define PG8_WAIT_L(n) asm volatile("s_waitcnt lgkmcnt(" #n ")" ::: "memory")
; #define PG8_BAR __builtin_amdgcn_s_barrier()
; template <class Epi, class Sched, bool ALIGN_EPI = false, bool SP2 = false, bool ABLK = false, bool BBLK = false>
; __device__ __forceinline__ void gemm_phase(PG8_LAS unsigned char* lds, const Gemm g, const Sched& S, const Epi& E) {
;     ...
;         const char* nA = has_next ? (const char*)g.A + (size_t)nxt.pm * tstep : cA; const char* nB = has_next ? (const char*)g.Bt + (size_t)nxt.pn * tstep : cB;
;         for (int t = 0; t < nt; t += 2) {
;             const bool last = (t == nt - 2);
;             const char* a1 = cA + (size_t)(t + 1) * kstepA;
;             const char* a2 = last ? nA : cA + (size_t)(t + 2) * kstepA; const char* b2 = last ? nB : cB + (size_t)(t + 2) * kstepB;
;             const char* a3 = a2 + kstepA; const char* b3 = b2 + kstepB;
;             if (last && has_next) S.a_ready(nxt);
;             if constexpr (SP2) {
;             PG8_LDB(B0, 0, 0); PG8_LDB(B1, 0, 1); PG8_SCHED; PG8_LDA(At, 0, 0); PG8_STAGE(PG8_SA(1, 1), a1 + hstepA, voffA);
;             PG8_WAIT_V(8); PG8_WAIT_L(0); PG8_BAR; PG8_MMA(0, 0, At, B0); PG8_MMA(0, 1, At, B1); PG8_BAR; PG8_SCHED;
;     ...
; #pragma unroll
;         for (int a = 0; a < 2; ++a)
; #pragma unroll
;             for (int b = 0; b < 2; ++b)
; #pragma unroll
;                 for (int m = 0; m < 4; ++m)
; #pragma unroll
;                     for (int n = 0; n < 2; ++n) acc[a][b][m][n] = (f32x4){0.f, 0.f, 0.f, 0.f};
;         cur = nxt; cA = nA; cB = nB; ++ui;
.LBB0_184:
	s_lshl_b32 s10, s18, 8
	s_ashr_i32 s11, s10, 31
	s_mov_b32 m0, s64
	v_lshl_add_u64 v[4:5], s[10:11], 2, v[144:145]
	global_load_lds_dword v[4:5], off
	v_lshl_add_u64 v[4:5], v[4:5], 0, s[90:91]
	s_add_i32 m0, s64, 0x100
	s_ashr_i32 s9, s8, 31
	global_load_lds_dword v[4:5], off
	s_lshl_b64 s[10:11], s[8:9], 20
	v_readlane_b32 s16, v252, 27
	v_readlane_b32 s17, v252, 28
	s_add_u32 s10, s16, s10
	s_addc_u32 s11, s17, s11
	s_and_b64 s[16:17], s[2:3], exec
	s_cselect_b32 s9, s11, s21
	s_cselect_b32 s70, s10, s20
	s_ashr_i32 s7, s6, 31
	s_lshl_b64 s[16:17], s[6:7], 20
	s_add_u32 s16, s29, s16
	s_addc_u32 s17, s30, s17
	s_and_b64 s[24:25], s[2:3], exec
	s_cselect_b32 s7, s17, s23
	s_cselect_b32 s71, s16, s22
	s_add_u32 s20, s20, 0xc000
	s_addc_u32 s21, s21, 0
	s_add_u32 s77, s22, 0x10000
	v_mov_b32_e32 v4, 0
	s_addc_u32 vcc_lo, s23, 0
	s_mov_b32 vcc_hi, -2
	v_readfirstlane_b32 s100, v0
	s_nop 3
	s_lshr_b32 s100, s100, 8
	s_cmp_eq_u32 s100, 0
	s_cbranch_scc1 .Lprio_done_0
	s_setprio 1
.Lprio_done_0:
	v_mov_b32_e32 v5, v4
	v_mov_b64_e32 v[6:7], 0
	v_mov_b64_e32 v[8:9], 0
	v_mov_b64_e32 v[10:11], 0
	v_mov_b64_e32 v[20:21], 0
	v_mov_b64_e32 v[22:23], 0
	v_mov_b64_e32 v[24:25], 0
	v_mov_b64_e32 v[26:27], 0
	v_mov_b64_e32 v[40:41], 0
	v_mov_b64_e32 v[42:43], 0
	v_mov_b64_e32 v[44:45], 0
	v_mov_b64_e32 v[46:47], 0
	v_mov_b64_e32 v[56:57], 0
	v_mov_b64_e32 v[58:59], 0
	v_mov_b64_e32 v[60:61], 0
	v_mov_b64_e32 v[62:63], 0
	v_mov_b64_e32 v[12:13], 0
	v_mov_b64_e32 v[14:15], 0
	v_mov_b64_e32 v[16:17], 0
	v_mov_b64_e32 v[18:19], 0
	v_mov_b64_e32 v[28:29], 0
	v_mov_b64_e32 v[30:31], 0
	v_mov_b64_e32 v[32:33], 0
	v_mov_b64_e32 v[34:35], 0
	v_mov_b64_e32 v[48:49], 0
	v_mov_b64_e32 v[50:51], 0
	v_mov_b64_e32 v[52:53], 0
	v_mov_b64_e32 v[54:55], 0
	v_mov_b64_e32 v[64:65], 0
	v_mov_b64_e32 v[66:67], 0
	v_mov_b64_e32 v[68:69], 0
	v_mov_b64_e32 v[70:71], 0
	v_mov_b64_e32 v[72:73], 0
	v_mov_b64_e32 v[74:75], 0
	v_mov_b64_e32 v[76:77], 0
	v_mov_b64_e32 v[78:79], 0
	v_mov_b64_e32 v[88:89], 0
	v_mov_b64_e32 v[90:91], 0
	v_mov_b64_e32 v[92:93], 0
	v_mov_b64_e32 v[94:95], 0
	v_mov_b64_e32 v[104:105], 0
	v_mov_b64_e32 v[106:107], 0
	v_mov_b64_e32 v[108:109], 0
	v_mov_b64_e32 v[110:111], 0
	v_mov_b64_e32 v[120:121], 0
	v_mov_b64_e32 v[122:123], 0
	v_mov_b64_e32 v[124:125], 0
	v_mov_b64_e32 v[126:127], 0
	v_mov_b64_e32 v[80:81], 0
	v_mov_b64_e32 v[82:83], 0
	v_mov_b64_e32 v[84:85], 0
	v_mov_b64_e32 v[86:87], 0
	v_mov_b64_e32 v[96:97], 0
	v_mov_b64_e32 v[98:99], 0
	v_mov_b64_e32 v[100:101], 0
	v_mov_b64_e32 v[102:103], 0
	v_mov_b64_e32 v[112:113], 0
	v_mov_b64_e32 v[114:115], 0
	v_mov_b64_e32 v[116:117], 0
	v_mov_b64_e32 v[118:119], 0
	v_mov_b64_e32 v[128:129], 0
	v_mov_b64_e32 v[130:131], 0
	v_mov_b64_e32 v[132:133], 0
	v_mov_b64_e32 v[134:135], 0
.LBB0_185:
	s_add_u32 s13, s20, 0x4000
	s_addc_u32 s22, s21, 0
	s_cmp_eq_u32 vcc_hi, 28
	s_cselect_b32 s26, s70, s13
	s_cselect_b32 s27, s9, s22
	s_cselect_b32 s24, s71, s77
	s_cselect_b32 s25, s7, vcc_lo
	s_add_u32 s22, s26, 0x8000
	s_addc_u32 s23, s27, 0
	s_add_i32 s13, 0, 0x10000
	v_add_u32_e32 v36, s13, v160
	s_add_i32 s88, 0, 0x14000
	ds_read_b128 v[152:155], v36
	ds_read_b128 v[156:159], v36 offset:1024
	ds_read_b128 v[162:165], v36 offset:2048
	ds_read_b128 v[166:169], v36 offset:3072
	v_add_u32_e32 v36, s88, v160
	ds_read_b128 v[170:173], v36
	ds_read_b128 v[174:177], v36 offset:1024
	ds_read_b128 v[178:181], v36 offset:2048
	ds_read_b128 v[182:185], v36 offset:3072
	s_add_i32 m0, s19, 0xc000
	ds_read_b128 v[186:189], v161
	ds_read_b128 v[190:193], v161 offset:1024
	ds_read_b128 v[194:197], v161 offset:2048
	ds_read_b128 v[198:201], v161 offset:3072
	ds_read_b128 v[202:205], v161 offset:4096
	ds_read_b128 v[206:209], v161 offset:5120
	ds_read_b128 v[210:213], v161 offset:6144
	ds_read_b128 v[214:217], v161 offset:7168
	global_load_lds_dwordx4 v148, s[20:21]
	s_add_i32 m0, s19, 0xe000
	s_nop 0
	global_load_lds_dwordx4 v150, s[20:21]
	s_waitcnt vmcnt(8)
	s_waitcnt lgkmcnt(0)
	v_mfma_f32_16x16x32_bf16 v[132:135], v[152:155], v[186:189], v[132:135]
	v_mfma_f32_16x16x32_bf16 v[128:131], v[162:165], v[186:189], v[128:131]
	v_mfma_f32_16x16x32_bf16 v[116:119], v[152:155], v[194:197], v[116:119]
	v_mfma_f32_16x16x32_bf16 v[112:115], v[162:165], v[194:197], v[112:115]
	s_barrier
	v_mfma_f32_16x16x32_bf16 v[100:103], v[152:155], v[202:205], v[100:103]
	v_mfma_f32_16x16x32_bf16 v[96:99], v[162:165], v[202:205], v[96:99]
	v_mfma_f32_16x16x32_bf16 v[84:87], v[152:155], v[210:213], v[84:87]
	v_mfma_f32_16x16x32_bf16 v[80:83], v[162:165], v[210:213], v[80:83]
	v_mfma_f32_16x16x32_bf16 v[132:135], v[156:159], v[190:193], v[132:135]
	v_mfma_f32_16x16x32_bf16 v[128:131], v[166:169], v[190:193], v[128:131]
	v_mfma_f32_16x16x32_bf16 v[116:119], v[156:159], v[198:201], v[116:119]
	v_mfma_f32_16x16x32_bf16 v[112:115], v[166:169], v[198:201], v[112:115]
	v_mfma_f32_16x16x32_bf16 v[100:103], v[156:159], v[206:209], v[100:103]
	v_mfma_f32_16x16x32_bf16 v[96:99], v[166:169], v[206:209], v[96:99]
	v_mfma_f32_16x16x32_bf16 v[84:87], v[156:159], v[214:217], v[84:87]
	v_mfma_f32_16x16x32_bf16 v[80:83], v[166:169], v[214:217], v[80:83]
	v_mfma_f32_16x16x32_bf16 v[124:127], v[170:173], v[186:189], v[124:127]
	v_mfma_f32_16x16x32_bf16 v[120:123], v[178:181], v[186:189], v[120:123]
	v_mfma_f32_16x16x32_bf16 v[108:111], v[170:173], v[194:197], v[108:111]
	v_mfma_f32_16x16x32_bf16 v[104:107], v[178:181], v[194:197], v[104:107]
	v_mfma_f32_16x16x32_bf16 v[92:95], v[170:173], v[202:205], v[92:95]
	v_mfma_f32_16x16x32_bf16 v[88:91], v[178:181], v[202:205], v[88:91]
	v_mfma_f32_16x16x32_bf16 v[76:79], v[170:173], v[210:213], v[76:79]
	v_mfma_f32_16x16x32_bf16 v[72:75], v[178:181], v[210:213], v[72:75]
	v_mfma_f32_16x16x32_bf16 v[124:127], v[174:177], v[190:193], v[124:127]
	v_mfma_f32_16x16x32_bf16 v[120:123], v[182:185], v[190:193], v[120:123]
	v_mfma_f32_16x16x32_bf16 v[108:111], v[174:177], v[198:201], v[108:111]
	v_mfma_f32_16x16x32_bf16 v[104:107], v[182:185], v[198:201], v[104:107]
	v_mfma_f32_16x16x32_bf16 v[92:95], v[174:177], v[206:209], v[92:95]
	v_mfma_f32_16x16x32_bf16 v[88:91], v[182:185], v[206:209], v[88:91]
	v_mfma_f32_16x16x32_bf16 v[76:79], v[174:177], v[214:217], v[76:79]
	v_mfma_f32_16x16x32_bf16 v[72:75], v[182:185], v[214:217], v[72:75]
	s_barrier
; #define PG8_STAGE(bufoff, gbase, voff) do { _Pragma("unroll") for (int _i = 0; _i < 2; ++_i) \
;         __builtin_amdgcn_global_load_lds((const unsigned*)((const char*)(gbase) + (voff)[_i]), (PG8_LAS unsigned*)(lds + (bufoff) + ldsw + _i * 8192), 16, 0, 0); } while (0)
; #define PG8_LDA(dst, b, h) do { _Pragma("unroll") for (int m = 0; m < 4; ++m) _Pragma("unroll") for (int k = 0; k < 2; ++k) dst[m][k] = *(const PG8_LAS bf16x8*)(lds + PG8_SA(b, h) + aoff + m * 2048 + k * 1024); } while (0)
; #define PG8_LDB(dst, b, h) do { _Pragma("unroll") for (int n = 0; n < 2; ++n) _Pragma("unroll") for (int k = 0; k < 2; ++k) dst[n][k] = *(const PG8_LAS bf16x8*)(lds + PG8_SB(b, h) + boff + n * 2048 + k * 1024); } while (0)
; #define PG8_MMA(ai, bj, At, Bt) do { __builtin_amdgcn_s_setprio(1); _Pragma("unroll") for (int m = 0; m < 4; ++m) _Pragma("unroll") for (int n = 0; n < 2; ++n) _Pragma("unroll") for (int k = 0; k < 2; ++k) \
;         acc[ai][bj][m][n] = __builtin_amdgcn_mfma_f32_16x16x32_bf16(Bt[n][k], At[m][k], acc[ai][bj][m][n], 0, 0, 0); __builtin_amdgcn_s_setprio(0); } while (0)
; #define PG8_WAIT_V(n) asm volatile("s_waitcnt vmcnt(" #n ")" ::: "memory")
; #define PG8_WAIT_L(n) asm volatile("s_waitcnt lgkmcnt(" #n ")" ::: "memory")
; #define PG8_BAR __builtin_amdgcn_s_barrier()
; #define PG8_SCHED __builtin_amdgcn_sched_barrier(0)
; template <class Epi, class Sched, bool ALIGN_EPI = false, bool SP2 = false, bool ABLK = false, bool BBLK = false>
; __device__ __forceinline__ void gemm_phase(PG8_LAS unsigned char* lds, const Gemm g, const Sched& S, const Epi& E) {
;     ...
;             PG8_WAIT_V(8); PG8_WAIT_L(0); PG8_BAR; PG8_MMA(0, 0, At, B0); PG8_MMA(0, 1, At, B1); PG8_BAR; PG8_SCHED;
;             PG8_LDA(At, 0, 1); PG8_STAGE(PG8_SB(0, 0), b2, voffB); PG8_STAGE(PG8_SB(0, 1), b2 + hstepB, voffB); PG8_STAGE(PG8_SA(0, 0), a2, voffA);
;             PG8_WAIT_V(8); PG8_WAIT_L(0); PG8_BAR; PG8_MMA(1, 0, At, B0); PG8_MMA(1, 1, At, B1); PG8_BAR; PG8_SCHED;
;             PG8_LDB(B0, 1, 0); PG8_LDB(B1, 1, 1); PG8_SCHED; PG8_LDA(At, 1, 0); PG8_STAGE(PG8_SA(0, 1), a2 + hstepA, voffA);
	s_add_i32 s13, s13, s31
	s_mov_b32 m0, s13
	ds_read_b128 v[186:189], v161 offset:16384
	ds_read_b128 v[190:193], v161 offset:17408
	ds_read_b128 v[194:197], v161 offset:18432
	ds_read_b128 v[198:201], v161 offset:19456
	ds_read_b128 v[202:205], v161 offset:20480
	ds_read_b128 v[206:209], v161 offset:21504
	ds_read_b128 v[210:213], v161 offset:22528
	ds_read_b128 v[214:217], v161 offset:23552
	global_load_lds_dwordx4 v140, s[24:25]
	s_add_i32 m0, s13, 0x2000
	s_add_u32 s68, s24, 0x4000
	s_addc_u32 s69, s25, 0
	s_add_i32 s13, s88, s31
	global_load_lds_dwordx4 v136, s[24:25]
	s_mov_b32 m0, s13
	s_nop 0
	global_load_lds_dwordx4 v140, s[68:69]
	s_add_i32 m0, s13, 0x2000
	s_nop 0
	global_load_lds_dwordx4 v136, s[68:69]
	s_mov_b32 m0, s19
	s_nop 0
	global_load_lds_dwordx4 v142, s[26:27]
	s_mov_b32 m0, s35
	s_nop 0
	global_load_lds_dwordx4 v138, s[26:27]
	s_waitcnt vmcnt(8)
	s_waitcnt lgkmcnt(0)
	v_mfma_f32_16x16x32_bf16 v[68:71], v[152:155], v[186:189], v[68:71]
	v_mfma_f32_16x16x32_bf16 v[64:67], v[162:165], v[186:189], v[64:67]
	v_mfma_f32_16x16x32_bf16 v[52:55], v[152:155], v[194:197], v[52:55]
	v_mfma_f32_16x16x32_bf16 v[48:51], v[162:165], v[194:197], v[48:51]
	s_barrier
	v_mfma_f32_16x16x32_bf16 v[32:35], v[152:155], v[202:205], v[32:35]
	v_mfma_f32_16x16x32_bf16 v[28:31], v[162:165], v[202:205], v[28:31]
	v_mfma_f32_16x16x32_bf16 v[16:19], v[152:155], v[210:213], v[16:19]
	v_mfma_f32_16x16x32_bf16 v[12:15], v[162:165], v[210:213], v[12:15]
	v_mfma_f32_16x16x32_bf16 v[68:71], v[156:159], v[190:193], v[68:71]
	v_mfma_f32_16x16x32_bf16 v[64:67], v[166:169], v[190:193], v[64:67]
	v_mfma_f32_16x16x32_bf16 v[52:55], v[156:159], v[198:201], v[52:55]
	v_mfma_f32_16x16x32_bf16 v[48:51], v[166:169], v[198:201], v[48:51]
	v_mfma_f32_16x16x32_bf16 v[32:35], v[156:159], v[206:209], v[32:35]
	v_mfma_f32_16x16x32_bf16 v[28:31], v[166:169], v[206:209], v[28:31]
	v_mfma_f32_16x16x32_bf16 v[16:19], v[156:159], v[214:217], v[16:19]
	v_mfma_f32_16x16x32_bf16 v[12:15], v[166:169], v[214:217], v[12:15]
	v_mfma_f32_16x16x32_bf16 v[60:63], v[170:173], v[186:189], v[60:63]
	v_mfma_f32_16x16x32_bf16 v[56:59], v[178:181], v[186:189], v[56:59]
	v_mfma_f32_16x16x32_bf16 v[44:47], v[170:173], v[194:197], v[44:47]
	v_mfma_f32_16x16x32_bf16 v[40:43], v[178:181], v[194:197], v[40:43]
	v_mfma_f32_16x16x32_bf16 v[24:27], v[170:173], v[202:205], v[24:27]
	v_mfma_f32_16x16x32_bf16 v[20:23], v[178:181], v[202:205], v[20:23]
	v_mfma_f32_16x16x32_bf16 v[8:11], v[170:173], v[210:213], v[8:11]
	v_mfma_f32_16x16x32_bf16 v[4:7], v[178:181], v[210:213], v[4:7]
	v_mfma_f32_16x16x32_bf16 v[60:63], v[174:177], v[190:193], v[60:63]
	v_mfma_f32_16x16x32_bf16 v[56:59], v[182:185], v[190:193], v[56:59]
	v_mfma_f32_16x16x32_bf16 v[44:47], v[174:177], v[198:201], v[44:47]
	v_mfma_f32_16x16x32_bf16 v[40:43], v[182:185], v[198:201], v[40:43]
	v_mfma_f32_16x16x32_bf16 v[24:27], v[174:177], v[206:209], v[24:27]
	v_mfma_f32_16x16x32_bf16 v[20:23], v[182:185], v[206:209], v[20:23]
	v_mfma_f32_16x16x32_bf16 v[8:11], v[174:177], v[214:217], v[8:11]
	v_mfma_f32_16x16x32_bf16 v[4:7], v[182:185], v[214:217], v[4:7]
	s_barrier
	s_add_i32 s13, 0, 0x18000
	v_add_u32_e32 v36, s13, v160
	s_add_i32 s68, 0, 0x1c000
	ds_read_b128 v[152:155], v36
	ds_read_b128 v[156:159], v36 offset:1024
	ds_read_b128 v[162:165], v36 offset:2048
	ds_read_b128 v[166:169], v36 offset:3072
	v_add_u32_e32 v36, s68, v160
	ds_read_b128 v[170:173], v36
	ds_read_b128 v[174:177], v36 offset:1024
	ds_read_b128 v[178:181], v36 offset:2048
	ds_read_b128 v[182:185], v36 offset:3072
	s_add_u32 s26, s26, 0x4000
	s_addc_u32 s27, s27, 0
	s_mov_b32 m0, s36
	ds_read_b128 v[186:189], v161 offset:32768
	ds_read_b128 v[190:193], v161 offset:33792
	ds_read_b128 v[194:197], v161 offset:34816
	ds_read_b128 v[198:201], v161 offset:35840
	ds_read_b128 v[202:205], v161 offset:36864
	ds_read_b128 v[206:209], v161 offset:37888
	ds_read_b128 v[210:213], v161 offset:38912
	ds_read_b128 v[214:217], v161 offset:39936
	global_load_lds_dwordx4 v142, s[26:27]
	s_mov_b32 m0, s37
	s_nop 0
	global_load_lds_dwordx4 v138, s[26:27]
	s_waitcnt vmcnt(8)
	s_waitcnt lgkmcnt(0)
	v_mfma_f32_16x16x32_bf16 v[132:135], v[152:155], v[186:189], v[132:135]
	v_mfma_f32_16x16x32_bf16 v[128:131], v[162:165], v[186:189], v[128:131]
	v_mfma_f32_16x16x32_bf16 v[116:119], v[152:155], v[194:197], v[116:119]
	v_mfma_f32_16x16x32_bf16 v[112:115], v[162:165], v[194:197], v[112:115]
	s_barrier
; #define PG8_STAGE(bufoff, gbase, voff) do { _Pragma("unroll") for (int _i = 0; _i < 2; ++_i) \
;         __builtin_amdgcn_global_load_lds((const unsigned*)((const char*)(gbase) + (voff)[_i]), (PG8_LAS unsigned*)(lds + (bufoff) + ldsw + _i * 8192), 16, 0, 0); } while (0)
; #define PG8_LDA(dst, b, h) do { _Pragma("unroll") for (int m = 0; m < 4; ++m) _Pragma("unroll") for (int k = 0; k < 2; ++k) dst[m][k] = *(const PG8_LAS bf16x8*)(lds + PG8_SA(b, h) + aoff + m * 2048 + k * 1024); } while (0)
; #define PG8_MMA(ai, bj, At, Bt) do { __builtin_amdgcn_s_setprio(1); _Pragma("unroll") for (int m = 0; m < 4; ++m) _Pragma("unroll") for (int n = 0; n < 2; ++n) _Pragma("unroll") for (int k = 0; k < 2; ++k) \
;         acc[ai][bj][m][n] = __builtin_amdgcn_mfma_f32_16x16x32_bf16(Bt[n][k], At[m][k], acc[ai][bj][m][n], 0, 0, 0); __builtin_amdgcn_s_setprio(0); } while (0)
; #define PG8_WAIT_V(n) asm volatile("s_waitcnt vmcnt(" #n ")" ::: "memory")
; #define PG8_WAIT_L(n) asm volatile("s_waitcnt lgkmcnt(" #n ")" ::: "memory")
; #define PG8_BAR __builtin_amdgcn_s_barrier()
; #define PG8_SCHED __builtin_amdgcn_sched_barrier(0)
; template <class Epi, class Sched, bool ALIGN_EPI = false, bool SP2 = false, bool ABLK = false, bool BBLK = false>
; __device__ __forceinline__ void gemm_phase(PG8_LAS unsigned char* lds, const Gemm g, const Sched& S, const Epi& E) {
;     ...
;             PG8_WAIT_V(8); PG8_WAIT_L(0); PG8_BAR; PG8_MMA(0, 0, At, B0); PG8_MMA(0, 1, At, B1); PG8_BAR; PG8_SCHED;
;             PG8_LDA(At, 1, 1); PG8_STAGE(PG8_SB(1, 0), b3, voffB); PG8_STAGE(PG8_SB(1, 1), b3 + hstepB, voffB); PG8_STAGE(PG8_SA(1, 0), a3, voffA);
;             PG8_WAIT_V(8); PG8_WAIT_L(0); PG8_BAR; PG8_MMA(1, 0, At, B0); PG8_MMA(1, 1, At, B1); PG8_BAR; PG8_SCHED;
;     ...
;         if constexpr (ALIGN_EPI) { if (wr == 0) PG8_BAR; }
	v_mfma_f32_16x16x32_bf16 v[100:103], v[152:155], v[202:205], v[100:103]
	v_mfma_f32_16x16x32_bf16 v[96:99], v[162:165], v[202:205], v[96:99]
	v_mfma_f32_16x16x32_bf16 v[84:87], v[152:155], v[210:213], v[84:87]
	v_mfma_f32_16x16x32_bf16 v[80:83], v[162:165], v[210:213], v[80:83]
	v_mfma_f32_16x16x32_bf16 v[132:135], v[156:159], v[190:193], v[132:135]
	v_mfma_f32_16x16x32_bf16 v[128:131], v[166:169], v[190:193], v[128:131]
	v_mfma_f32_16x16x32_bf16 v[116:119], v[156:159], v[198:201], v[116:119]
	v_mfma_f32_16x16x32_bf16 v[112:115], v[166:169], v[198:201], v[112:115]
	v_mfma_f32_16x16x32_bf16 v[100:103], v[156:159], v[206:209], v[100:103]
	v_mfma_f32_16x16x32_bf16 v[96:99], v[166:169], v[206:209], v[96:99]
	v_mfma_f32_16x16x32_bf16 v[84:87], v[156:159], v[214:217], v[84:87]
	v_mfma_f32_16x16x32_bf16 v[80:83], v[166:169], v[214:217], v[80:83]
	v_mfma_f32_16x16x32_bf16 v[124:127], v[170:173], v[186:189], v[124:127]
	v_mfma_f32_16x16x32_bf16 v[120:123], v[178:181], v[186:189], v[120:123]
	v_mfma_f32_16x16x32_bf16 v[108:111], v[170:173], v[194:197], v[108:111]
	v_mfma_f32_16x16x32_bf16 v[104:107], v[178:181], v[194:197], v[104:107]
	v_mfma_f32_16x16x32_bf16 v[92:95], v[170:173], v[202:205], v[92:95]
	v_mfma_f32_16x16x32_bf16 v[88:91], v[178:181], v[202:205], v[88:91]
	v_mfma_f32_16x16x32_bf16 v[76:79], v[170:173], v[210:213], v[76:79]
	v_mfma_f32_16x16x32_bf16 v[72:75], v[178:181], v[210:213], v[72:75]
	v_mfma_f32_16x16x32_bf16 v[124:127], v[174:177], v[190:193], v[124:127]
	v_mfma_f32_16x16x32_bf16 v[120:123], v[182:185], v[190:193], v[120:123]
	v_mfma_f32_16x16x32_bf16 v[108:111], v[174:177], v[198:201], v[108:111]
	v_mfma_f32_16x16x32_bf16 v[104:107], v[182:185], v[198:201], v[104:107]
	v_mfma_f32_16x16x32_bf16 v[92:95], v[174:177], v[206:209], v[92:95]
	v_mfma_f32_16x16x32_bf16 v[88:91], v[182:185], v[206:209], v[88:91]
	v_mfma_f32_16x16x32_bf16 v[76:79], v[174:177], v[214:217], v[76:79]
	v_mfma_f32_16x16x32_bf16 v[72:75], v[182:185], v[214:217], v[72:75]
	s_barrier
	s_add_u32 s26, s24, 0x8000
	s_addc_u32 s27, s25, 0
	s_add_i32 s13, s13, s31
	s_mov_b32 m0, s13
	ds_read_b128 v[186:189], v161 offset:49152
	ds_read_b128 v[190:193], v161 offset:50176
	ds_read_b128 v[194:197], v161 offset:51200
	ds_read_b128 v[198:201], v161 offset:52224
	ds_read_b128 v[202:205], v161 offset:53248
	ds_read_b128 v[206:209], v161 offset:54272
	ds_read_b128 v[210:213], v161 offset:55296
	ds_read_b128 v[214:217], v161 offset:56320
	global_load_lds_dwordx4 v140, s[26:27]
	s_add_i32 m0, s13, 0x2000
	s_add_u32 s24, s24, 0xc000
	s_addc_u32 s25, s25, 0
	s_add_i32 s13, s68, s31
	global_load_lds_dwordx4 v136, s[26:27]
	s_mov_b32 m0, s13
	s_nop 0
	global_load_lds_dwordx4 v140, s[24:25]
	s_add_i32 m0, s13, 0x2000
	s_nop 0
	global_load_lds_dwordx4 v136, s[24:25]
	s_mov_b32 m0, s62
	s_nop 0
	global_load_lds_dwordx4 v142, s[22:23]
	s_mov_b32 m0, s63
	s_nop 0
	global_load_lds_dwordx4 v138, s[22:23]
	s_waitcnt vmcnt(8)
	s_waitcnt lgkmcnt(0)
	v_mfma_f32_16x16x32_bf16 v[68:71], v[152:155], v[186:189], v[68:71]
	v_mfma_f32_16x16x32_bf16 v[64:67], v[162:165], v[186:189], v[64:67]
	v_mfma_f32_16x16x32_bf16 v[52:55], v[152:155], v[194:197], v[52:55]
	v_mfma_f32_16x16x32_bf16 v[48:51], v[162:165], v[194:197], v[48:51]
	s_barrier
	v_mfma_f32_16x16x32_bf16 v[32:35], v[152:155], v[202:205], v[32:35]
	v_mfma_f32_16x16x32_bf16 v[28:31], v[162:165], v[202:205], v[28:31]
	v_mfma_f32_16x16x32_bf16 v[16:19], v[152:155], v[210:213], v[16:19]
	v_mfma_f32_16x16x32_bf16 v[12:15], v[162:165], v[210:213], v[12:15]
	v_mfma_f32_16x16x32_bf16 v[68:71], v[156:159], v[190:193], v[68:71]
	v_mfma_f32_16x16x32_bf16 v[64:67], v[166:169], v[190:193], v[64:67]
	v_mfma_f32_16x16x32_bf16 v[52:55], v[156:159], v[198:201], v[52:55]
	v_mfma_f32_16x16x32_bf16 v[48:51], v[166:169], v[198:201], v[48:51]
	v_mfma_f32_16x16x32_bf16 v[32:35], v[156:159], v[206:209], v[32:35]
	v_mfma_f32_16x16x32_bf16 v[28:31], v[166:169], v[206:209], v[28:31]
	v_mfma_f32_16x16x32_bf16 v[16:19], v[156:159], v[214:217], v[16:19]
	v_mfma_f32_16x16x32_bf16 v[12:15], v[166:169], v[214:217], v[12:15]
	v_mfma_f32_16x16x32_bf16 v[60:63], v[170:173], v[186:189], v[60:63]
	v_mfma_f32_16x16x32_bf16 v[56:59], v[178:181], v[186:189], v[56:59]
	v_mfma_f32_16x16x32_bf16 v[44:47], v[170:173], v[194:197], v[44:47]
	v_mfma_f32_16x16x32_bf16 v[40:43], v[178:181], v[194:197], v[40:43]
	v_mfma_f32_16x16x32_bf16 v[24:27], v[170:173], v[202:205], v[24:27]
	v_mfma_f32_16x16x32_bf16 v[20:23], v[178:181], v[202:205], v[20:23]
	v_mfma_f32_16x16x32_bf16 v[8:11], v[170:173], v[210:213], v[8:11]
	v_mfma_f32_16x16x32_bf16 v[4:7], v[178:181], v[210:213], v[4:7]
	v_mfma_f32_16x16x32_bf16 v[60:63], v[174:177], v[190:193], v[60:63]
	v_mfma_f32_16x16x32_bf16 v[56:59], v[182:185], v[190:193], v[56:59]
	v_mfma_f32_16x16x32_bf16 v[44:47], v[174:177], v[198:201], v[44:47]
	v_mfma_f32_16x16x32_bf16 v[40:43], v[182:185], v[198:201], v[40:43]
	v_mfma_f32_16x16x32_bf16 v[24:27], v[174:177], v[206:209], v[24:27]
	v_mfma_f32_16x16x32_bf16 v[20:23], v[182:185], v[206:209], v[20:23]
	v_mfma_f32_16x16x32_bf16 v[8:11], v[174:177], v[214:217], v[8:11]
	v_mfma_f32_16x16x32_bf16 v[4:7], v[182:185], v[214:217], v[4:7]
	s_barrier
	s_add_i32 vcc_hi, vcc_hi, 2
	s_add_u32 s20, s20, 0x10000
	s_addc_u32 s21, s21, 0
	s_add_u32 s77, s77, 0x10000
	s_addc_u32 vcc_lo, vcc_lo, 0
	s_cmp_gt_u32 vcc_hi, 29
	s_cbranch_scc0 .LBB0_185
	s_setprio 0
	s_and_b64 vcc, exec, s[4:5]
	s_cbranch_vccz .LBB0_188
	s_barrier

; #define PG8_STAGE(bufoff, gbase, voff) do { _Pragma("unroll") for (int _i = 0; _i < 2; ++_i) \
;         __builtin_amdgcn_global_load_lds((const unsigned*)((const char*)(gbase) + (voff)[_i]), (PG8_LAS unsigned*)(lds + (bufoff) + ldsw + _i * 8192), 16, 0, 0); } while (0)
; #define PG8_LDA(dst, b, h) do { _Pragma("unroll") for (int m = 0; m < 4; ++m) _Pragma("unroll") for (int k = 0; k < 2; ++k) dst[m][k] = *(const PG8_LAS bf16x8*)(lds + PG8_SA(b, h) + aoff + m * 2048 + k * 1024); } while (0)
; #define PG8_LDB(dst, b, h) do { _Pragma("unroll") for (int n = 0; n < 2; ++n) _Pragma("unroll") for (int k = 0; k < 2; ++k) dst[n][k] = *(const PG8_LAS bf16x8*)(lds + PG8_SB(b, h) + boff + n * 2048 + k * 1024); } while (0)
; #define PG8_WAIT_V(n) asm volatile("s_waitcnt vmcnt(" #n ")" ::: "memory")
; #define PG8_WAIT_L(n) asm volatile("s_waitcnt lgkmcnt(" #n ")" ::: "memory")
; #define PG8_BAR __builtin_amdgcn_s_barrier()
; template <class Epi, class Sched, bool ALIGN_EPI = false, bool SP2 = false, bool ABLK = false, bool BBLK = false>
; __device__ __forceinline__ void gemm_phase(PG8_LAS unsigned char* lds, const Gemm g, const Sched& S, const Epi& E) {
;     ...
;         const char* nA = has_next ? (const char*)g.A + (size_t)nxt.pm * tstep : cA; const char* nB = has_next ? (const char*)g.Bt + (size_t)nxt.pn * tstep : cB;
;         for (int t = 0; t < nt; t += 2) {
;             const bool last = (t == nt - 2);
;             const char* a1 = cA + (size_t)(t + 1) * kstepA;
;             const char* a2 = last ? nA : cA + (size_t)(t + 2) * kstepA; const char* b2 = last ? nB : cB + (size_t)(t + 2) * kstepB;
;             const char* a3 = a2 + kstepA; const char* b3 = b2 + kstepB;
;             if (last && has_next) S.a_ready(nxt);
;             if constexpr (SP2) {
;             PG8_LDB(B0, 0, 0); PG8_LDB(B1, 0, 1); PG8_SCHED; PG8_LDA(At, 0, 0); PG8_STAGE(PG8_SA(1, 1), a1 + hstepA, voffA);
;             PG8_WAIT_V(8); PG8_WAIT_L(0); PG8_BAR; PG8_MMA(0, 0, At, B0); PG8_MMA(0, 1, At, B1); PG8_BAR; PG8_SCHED;
;     ...
; #pragma unroll
;         for (int a = 0; a < 2; ++a)
; #pragma unroll
;             for (int b = 0; b < 2; ++b)
; #pragma unroll
;                 for (int m = 0; m < 4; ++m)
; #pragma unroll
;                     for (int n = 0; n < 2; ++n) acc[a][b][m][n] = (f32x4){0.f, 0.f, 0.f, 0.f};
;         cur = nxt; cA = nA; cB = nB; ++ui;
.LBB0_438:
	s_add_u32 s10, s10, 0xc000
	s_addc_u32 s11, s11, 0
	s_add_u32 vcc_lo, s16, 0x10000
	v_mov_b32_e32 v4, 0
	s_addc_u32 vcc_hi, s17, 0
	s_mov_b32 s13, -2
	v_readfirstlane_b32 s100, v0
	s_nop 3
	s_lshr_b32 s100, s100, 8
	s_cmp_eq_u32 s100, 0
	s_cbranch_scc1 .Lprio_done_1
	s_setprio 1
.Lprio_done_1:
	v_mov_b32_e32 v5, v4
	v_mov_b64_e32 v[6:7], 0
	v_mov_b64_e32 v[8:9], 0
	v_mov_b64_e32 v[10:11], 0
	v_mov_b64_e32 v[12:13], 0
	v_mov_b64_e32 v[14:15], 0
	v_mov_b64_e32 v[16:17], 0
	v_mov_b64_e32 v[18:19], 0
	v_mov_b64_e32 v[28:29], 0
	v_mov_b64_e32 v[30:31], 0
	v_mov_b64_e32 v[32:33], 0
	v_mov_b64_e32 v[34:35], 0
	v_mov_b64_e32 v[48:49], 0
	v_mov_b64_e32 v[50:51], 0
	v_mov_b64_e32 v[52:53], 0
	v_mov_b64_e32 v[54:55], 0
	v_mov_b64_e32 v[20:21], 0
	v_mov_b64_e32 v[22:23], 0
	v_mov_b64_e32 v[24:25], 0
	v_mov_b64_e32 v[26:27], 0
	v_mov_b64_e32 v[40:41], 0
	v_mov_b64_e32 v[42:43], 0
	v_mov_b64_e32 v[44:45], 0
	v_mov_b64_e32 v[46:47], 0
	v_mov_b64_e32 v[56:57], 0
	v_mov_b64_e32 v[58:59], 0
	v_mov_b64_e32 v[60:61], 0
	v_mov_b64_e32 v[62:63], 0
	v_mov_b64_e32 v[64:65], 0
	v_mov_b64_e32 v[66:67], 0
	v_mov_b64_e32 v[68:69], 0
	v_mov_b64_e32 v[70:71], 0
	v_mov_b64_e32 v[72:73], 0
	v_mov_b64_e32 v[74:75], 0
	v_mov_b64_e32 v[76:77], 0
	v_mov_b64_e32 v[78:79], 0
	v_mov_b64_e32 v[80:81], 0
	v_mov_b64_e32 v[82:83], 0
	v_mov_b64_e32 v[84:85], 0
	v_mov_b64_e32 v[86:87], 0
	v_mov_b64_e32 v[96:97], 0
	v_mov_b64_e32 v[98:99], 0
	v_mov_b64_e32 v[100:101], 0
	v_mov_b64_e32 v[102:103], 0
	v_mov_b64_e32 v[112:113], 0
	v_mov_b64_e32 v[114:115], 0
	v_mov_b64_e32 v[116:117], 0
	v_mov_b64_e32 v[118:119], 0
	v_mov_b64_e32 v[88:89], 0
	v_mov_b64_e32 v[90:91], 0
	v_mov_b64_e32 v[92:93], 0
	v_mov_b64_e32 v[94:95], 0
	v_mov_b64_e32 v[104:105], 0
	v_mov_b64_e32 v[106:107], 0
	v_mov_b64_e32 v[108:109], 0
	v_mov_b64_e32 v[110:111], 0
	v_mov_b64_e32 v[120:121], 0
	v_mov_b64_e32 v[122:123], 0
	v_mov_b64_e32 v[124:125], 0
	v_mov_b64_e32 v[126:127], 0
	v_mov_b64_e32 v[128:129], 0
	v_mov_b64_e32 v[130:131], 0
	v_mov_b64_e32 v[132:133], 0
	v_mov_b64_e32 v[134:135], 0
.LBB0_439:
	s_add_u32 s16, s10, 0x4000
	s_addc_u32 s17, s11, 0
	s_cmpk_eq_i32 s13, 0x54
	s_cselect_b32 s20, s0, s16
	s_cselect_b32 s21, s1, s17
	s_cselect_b32 s18, s8, vcc_lo
	s_cselect_b32 s19, s9, vcc_hi
	s_add_u32 s16, s20, 0x8000
	s_addc_u32 s17, s21, 0
	s_add_i32 s68, 0, 0x10000
	v_add_u32_e32 v36, s68, v148
	s_add_i32 s88, 0, 0x14000
	ds_read_b128 v[152:155], v36
	ds_read_b128 v[156:159], v36 offset:1024
	ds_read_b128 v[160:163], v36 offset:2048
	ds_read_b128 v[164:167], v36 offset:3072
	v_add_u32_e32 v36, s88, v148
	ds_read_b128 v[168:171], v36
	ds_read_b128 v[172:175], v36 offset:1024
	ds_read_b128 v[176:179], v36 offset:2048
	ds_read_b128 v[180:183], v36 offset:3072
	s_add_i32 m0, s27, 0xc000
	ds_read_b128 v[184:187], v150
	ds_read_b128 v[188:191], v150 offset:1024
	ds_read_b128 v[192:195], v150 offset:2048
	ds_read_b128 v[196:199], v150 offset:3072
	ds_read_b128 v[200:203], v150 offset:4096
	ds_read_b128 v[204:207], v150 offset:5120
	ds_read_b128 v[208:211], v150 offset:6144
	ds_read_b128 v[212:215], v150 offset:7168
	global_load_lds_dwordx4 v144, s[10:11]
	s_add_i32 m0, s27, 0xe000
	s_nop 0
	global_load_lds_dwordx4 v146, s[10:11]
	s_waitcnt vmcnt(8)
	s_waitcnt lgkmcnt(0)
	v_mfma_f32_16x16x32_bf16 v[132:135], v[152:155], v[184:187], v[132:135]
	v_mfma_f32_16x16x32_bf16 v[128:131], v[160:163], v[184:187], v[128:131]
	v_mfma_f32_16x16x32_bf16 v[124:127], v[152:155], v[192:195], v[124:127]
	v_mfma_f32_16x16x32_bf16 v[120:123], v[160:163], v[192:195], v[120:123]
	s_barrier
	v_mfma_f32_16x16x32_bf16 v[108:111], v[152:155], v[200:203], v[108:111]
	v_mfma_f32_16x16x32_bf16 v[104:107], v[160:163], v[200:203], v[104:107]
	v_mfma_f32_16x16x32_bf16 v[92:95], v[152:155], v[208:211], v[92:95]
	v_mfma_f32_16x16x32_bf16 v[88:91], v[160:163], v[208:211], v[88:91]
	v_mfma_f32_16x16x32_bf16 v[132:135], v[156:159], v[188:191], v[132:135]
	v_mfma_f32_16x16x32_bf16 v[128:131], v[164:167], v[188:191], v[128:131]
	v_mfma_f32_16x16x32_bf16 v[124:127], v[156:159], v[196:199], v[124:127]
	v_mfma_f32_16x16x32_bf16 v[120:123], v[164:167], v[196:199], v[120:123]
	v_mfma_f32_16x16x32_bf16 v[108:111], v[156:159], v[204:207], v[108:111]
	v_mfma_f32_16x16x32_bf16 v[104:107], v[164:167], v[204:207], v[104:107]
	v_mfma_f32_16x16x32_bf16 v[92:95], v[156:159], v[212:215], v[92:95]
	v_mfma_f32_16x16x32_bf16 v[88:91], v[164:167], v[212:215], v[88:91]
	v_mfma_f32_16x16x32_bf16 v[116:119], v[168:171], v[184:187], v[116:119]
	v_mfma_f32_16x16x32_bf16 v[112:115], v[176:179], v[184:187], v[112:115]
	v_mfma_f32_16x16x32_bf16 v[100:103], v[168:171], v[192:195], v[100:103]
	v_mfma_f32_16x16x32_bf16 v[96:99], v[176:179], v[192:195], v[96:99]
	v_mfma_f32_16x16x32_bf16 v[84:87], v[168:171], v[200:203], v[84:87]
	v_mfma_f32_16x16x32_bf16 v[80:83], v[176:179], v[200:203], v[80:83]
	v_mfma_f32_16x16x32_bf16 v[76:79], v[168:171], v[208:211], v[76:79]
	v_mfma_f32_16x16x32_bf16 v[72:75], v[176:179], v[208:211], v[72:75]
	v_mfma_f32_16x16x32_bf16 v[116:119], v[172:175], v[188:191], v[116:119]
	v_mfma_f32_16x16x32_bf16 v[112:115], v[180:183], v[188:191], v[112:115]
	v_mfma_f32_16x16x32_bf16 v[100:103], v[172:175], v[196:199], v[100:103]
	v_mfma_f32_16x16x32_bf16 v[96:99], v[180:183], v[196:199], v[96:99]
	v_mfma_f32_16x16x32_bf16 v[84:87], v[172:175], v[204:207], v[84:87]
	v_mfma_f32_16x16x32_bf16 v[80:83], v[180:183], v[204:207], v[80:83]
	v_mfma_f32_16x16x32_bf16 v[76:79], v[172:175], v[212:215], v[76:79]
	v_mfma_f32_16x16x32_bf16 v[72:75], v[180:183], v[212:215], v[72:75]
	s_barrier
; #define PG8_STAGE(bufoff, gbase, voff) do { _Pragma("unroll") for (int _i = 0; _i < 2; ++_i) \
;         __builtin_amdgcn_global_load_lds((const unsigned*)((const char*)(gbase) + (voff)[_i]), (PG8_LAS unsigned*)(lds + (bufoff) + ldsw + _i * 8192), 16, 0, 0); } while (0)
; #define PG8_LDA(dst, b, h) do { _Pragma("unroll") for (int m = 0; m < 4; ++m) _Pragma("unroll") for (int k = 0; k < 2; ++k) dst[m][k] = *(const PG8_LAS bf16x8*)(lds + PG8_SA(b, h) + aoff + m * 2048 + k * 1024); } while (0)
; #define PG8_LDB(dst, b, h) do { _Pragma("unroll") for (int n = 0; n < 2; ++n) _Pragma("unroll") for (int k = 0; k < 2; ++k) dst[n][k] = *(const PG8_LAS bf16x8*)(lds + PG8_SB(b, h) + boff + n * 2048 + k * 1024); } while (0)
; #define PG8_MMA(ai, bj, At, Bt) do { __builtin_amdgcn_s_setprio(1); _Pragma("unroll") for (int m = 0; m < 4; ++m) _Pragma("unroll") for (int n = 0; n < 2; ++n) _Pragma("unroll") for (int k = 0; k < 2; ++k) \
;         acc[ai][bj][m][n] = __builtin_amdgcn_mfma_f32_16x16x32_bf16(Bt[n][k], At[m][k], acc[ai][bj][m][n], 0, 0, 0); __builtin_amdgcn_s_setprio(0); } while (0)
; #define PG8_WAIT_V(n) asm volatile("s_waitcnt vmcnt(" #n ")" ::: "memory")
; #define PG8_WAIT_L(n) asm volatile("s_waitcnt lgkmcnt(" #n ")" ::: "memory")
; #define PG8_BAR __builtin_amdgcn_s_barrier()
; #define PG8_SCHED __builtin_amdgcn_sched_barrier(0)
; template <class Epi, class Sched, bool ALIGN_EPI = false, bool SP2 = false, bool ABLK = false, bool BBLK = false>
; __device__ __forceinline__ void gemm_phase(PG8_LAS unsigned char* lds, const Gemm g, const Sched& S, const Epi& E) {
;     ...
;             PG8_WAIT_V(8); PG8_WAIT_L(0); PG8_BAR; PG8_MMA(0, 0, At, B0); PG8_MMA(0, 1, At, B1); PG8_BAR; PG8_SCHED;
;             PG8_LDA(At, 0, 1); PG8_STAGE(PG8_SB(0, 0), b2, voffB); PG8_STAGE(PG8_SB(0, 1), b2 + hstepB, voffB); PG8_STAGE(PG8_SA(0, 0), a2, voffA);
;             PG8_WAIT_V(8); PG8_WAIT_L(0); PG8_BAR; PG8_MMA(1, 0, At, B0); PG8_MMA(1, 1, At, B1); PG8_BAR; PG8_SCHED;
;             PG8_LDB(B0, 1, 0); PG8_LDB(B1, 1, 1); PG8_SCHED; PG8_LDA(At, 1, 0); PG8_STAGE(PG8_SA(0, 1), a2 + hstepA, voffA);
	s_add_i32 s68, s68, s24
	s_mov_b32 m0, s68
	ds_read_b128 v[184:187], v150 offset:16384
	ds_read_b128 v[188:191], v150 offset:17408
	ds_read_b128 v[192:195], v150 offset:18432
	ds_read_b128 v[196:199], v150 offset:19456
	ds_read_b128 v[200:203], v150 offset:20480
	ds_read_b128 v[204:207], v150 offset:21504
	ds_read_b128 v[208:211], v150 offset:22528
	ds_read_b128 v[212:215], v150 offset:23552
	global_load_lds_dwordx4 v138, s[18:19]
	s_add_i32 m0, s68, 0x2000
	s_add_u32 s68, s18, 0x4000
	s_addc_u32 s69, s19, 0
	s_add_i32 s88, s88, s24
	global_load_lds_dwordx4 v142, s[18:19]
	s_mov_b32 m0, s88
	s_nop 0
	global_load_lds_dwordx4 v138, s[68:69]
	s_add_i32 m0, s88, 0x2000
	s_nop 0
	global_load_lds_dwordx4 v142, s[68:69]
	s_mov_b32 m0, s27
	s_nop 0
	global_load_lds_dwordx4 v136, s[20:21]
	s_mov_b32 m0, s28
	s_nop 0
	global_load_lds_dwordx4 v140, s[20:21]
	s_waitcnt vmcnt(8)
	s_waitcnt lgkmcnt(0)
	v_mfma_f32_16x16x32_bf16 v[68:71], v[152:155], v[184:187], v[68:71]
	v_mfma_f32_16x16x32_bf16 v[64:67], v[160:163], v[184:187], v[64:67]
	v_mfma_f32_16x16x32_bf16 v[60:63], v[152:155], v[192:195], v[60:63]
	v_mfma_f32_16x16x32_bf16 v[56:59], v[160:163], v[192:195], v[56:59]
	s_barrier
	v_mfma_f32_16x16x32_bf16 v[44:47], v[152:155], v[200:203], v[44:47]
	v_mfma_f32_16x16x32_bf16 v[40:43], v[160:163], v[200:203], v[40:43]
	v_mfma_f32_16x16x32_bf16 v[24:27], v[152:155], v[208:211], v[24:27]
	v_mfma_f32_16x16x32_bf16 v[20:23], v[160:163], v[208:211], v[20:23]
	v_mfma_f32_16x16x32_bf16 v[68:71], v[156:159], v[188:191], v[68:71]
	v_mfma_f32_16x16x32_bf16 v[64:67], v[164:167], v[188:191], v[64:67]
	v_mfma_f32_16x16x32_bf16 v[60:63], v[156:159], v[196:199], v[60:63]
	v_mfma_f32_16x16x32_bf16 v[56:59], v[164:167], v[196:199], v[56:59]
	v_mfma_f32_16x16x32_bf16 v[44:47], v[156:159], v[204:207], v[44:47]
	v_mfma_f32_16x16x32_bf16 v[40:43], v[164:167], v[204:207], v[40:43]
	v_mfma_f32_16x16x32_bf16 v[24:27], v[156:159], v[212:215], v[24:27]
	v_mfma_f32_16x16x32_bf16 v[20:23], v[164:167], v[212:215], v[20:23]
	v_mfma_f32_16x16x32_bf16 v[52:55], v[168:171], v[184:187], v[52:55]
	v_mfma_f32_16x16x32_bf16 v[48:51], v[176:179], v[184:187], v[48:51]
	v_mfma_f32_16x16x32_bf16 v[32:35], v[168:171], v[192:195], v[32:35]
	v_mfma_f32_16x16x32_bf16 v[28:31], v[176:179], v[192:195], v[28:31]
	v_mfma_f32_16x16x32_bf16 v[16:19], v[168:171], v[200:203], v[16:19]
	v_mfma_f32_16x16x32_bf16 v[12:15], v[176:179], v[200:203], v[12:15]
	v_mfma_f32_16x16x32_bf16 v[8:11], v[168:171], v[208:211], v[8:11]
	v_mfma_f32_16x16x32_bf16 v[4:7], v[176:179], v[208:211], v[4:7]
	v_mfma_f32_16x16x32_bf16 v[52:55], v[172:175], v[188:191], v[52:55]
	v_mfma_f32_16x16x32_bf16 v[48:51], v[180:183], v[188:191], v[48:51]
	v_mfma_f32_16x16x32_bf16 v[32:35], v[172:175], v[196:199], v[32:35]
	v_mfma_f32_16x16x32_bf16 v[28:31], v[180:183], v[196:199], v[28:31]
	v_mfma_f32_16x16x32_bf16 v[16:19], v[172:175], v[204:207], v[16:19]
	v_mfma_f32_16x16x32_bf16 v[12:15], v[180:183], v[204:207], v[12:15]
	v_mfma_f32_16x16x32_bf16 v[8:11], v[172:175], v[212:215], v[8:11]
	v_mfma_f32_16x16x32_bf16 v[4:7], v[180:183], v[212:215], v[4:7]
	s_barrier
	s_add_i32 s68, 0, 0x18000
	v_add_u32_e32 v36, s68, v148
	s_add_i32 s69, 0, 0x1c000
	ds_read_b128 v[152:155], v36
	ds_read_b128 v[156:159], v36 offset:1024
	ds_read_b128 v[160:163], v36 offset:2048
	ds_read_b128 v[164:167], v36 offset:3072
	v_add_u32_e32 v36, s69, v148
	ds_read_b128 v[168:171], v36
	ds_read_b128 v[172:175], v36 offset:1024
	ds_read_b128 v[176:179], v36 offset:2048
	ds_read_b128 v[180:183], v36 offset:3072
	s_add_u32 s20, s20, 0x4000
	s_addc_u32 s21, s21, 0
	s_mov_b32 m0, s29
	ds_read_b128 v[184:187], v150 offset:32768
	ds_read_b128 v[188:191], v150 offset:33792
	ds_read_b128 v[192:195], v150 offset:34816
	ds_read_b128 v[196:199], v150 offset:35840
	ds_read_b128 v[200:203], v150 offset:36864
	ds_read_b128 v[204:207], v150 offset:37888
	ds_read_b128 v[208:211], v150 offset:38912
	ds_read_b128 v[212:215], v150 offset:39936
	global_load_lds_dwordx4 v136, s[20:21]
	s_mov_b32 m0, s30
	s_nop 0
	global_load_lds_dwordx4 v140, s[20:21]
	s_waitcnt vmcnt(8)
	s_waitcnt lgkmcnt(0)
	v_mfma_f32_16x16x32_bf16 v[132:135], v[152:155], v[184:187], v[132:135]
	v_mfma_f32_16x16x32_bf16 v[128:131], v[160:163], v[184:187], v[128:131]
	v_mfma_f32_16x16x32_bf16 v[124:127], v[152:155], v[192:195], v[124:127]
	v_mfma_f32_16x16x32_bf16 v[120:123], v[160:163], v[192:195], v[120:123]
	s_barrier
; #define PG8_STAGE(bufoff, gbase, voff) do { _Pragma("unroll") for (int _i = 0; _i < 2; ++_i) \
;         __builtin_amdgcn_global_load_lds((const unsigned*)((const char*)(gbase) + (voff)[_i]), (PG8_LAS unsigned*)(lds + (bufoff) + ldsw + _i * 8192), 16, 0, 0); } while (0)
; #define PG8_LDA(dst, b, h) do { _Pragma("unroll") for (int m = 0; m < 4; ++m) _Pragma("unroll") for (int k = 0; k < 2; ++k) dst[m][k] = *(const PG8_LAS bf16x8*)(lds + PG8_SA(b, h) + aoff + m * 2048 + k * 1024); } while (0)
; #define PG8_MMA(ai, bj, At, Bt) do { __builtin_amdgcn_s_setprio(1); _Pragma("unroll") for (int m = 0; m < 4; ++m) _Pragma("unroll") for (int n = 0; n < 2; ++n) _Pragma("unroll") for (int k = 0; k < 2; ++k) \
;         acc[ai][bj][m][n] = __builtin_amdgcn_mfma_f32_16x16x32_bf16(Bt[n][k], At[m][k], acc[ai][bj][m][n], 0, 0, 0); __builtin_amdgcn_s_setprio(0); } while (0)
; #define PG8_WAIT_V(n) asm volatile("s_waitcnt vmcnt(" #n ")" ::: "memory")
; #define PG8_WAIT_L(n) asm volatile("s_waitcnt lgkmcnt(" #n ")" ::: "memory")
; #define PG8_BAR __builtin_amdgcn_s_barrier()
; #define PG8_SCHED __builtin_amdgcn_sched_barrier(0)
; template <class Epi, class Sched, bool ALIGN_EPI = false, bool SP2 = false, bool ABLK = false, bool BBLK = false>
; __device__ __forceinline__ void gemm_phase(PG8_LAS unsigned char* lds, const Gemm g, const Sched& S, const Epi& E) {
;     ...
;             PG8_WAIT_V(8); PG8_WAIT_L(0); PG8_BAR; PG8_MMA(0, 0, At, B0); PG8_MMA(0, 1, At, B1); PG8_BAR; PG8_SCHED;
;             PG8_LDA(At, 1, 1); PG8_STAGE(PG8_SB(1, 0), b3, voffB); PG8_STAGE(PG8_SB(1, 1), b3 + hstepB, voffB); PG8_STAGE(PG8_SA(1, 0), a3, voffA);
;             PG8_WAIT_V(8); PG8_WAIT_L(0); PG8_BAR; PG8_MMA(1, 0, At, B0); PG8_MMA(1, 1, At, B1); PG8_BAR; PG8_SCHED;
;     ...
;         if constexpr (ALIGN_EPI) { if (wr == 0) PG8_BAR; }
	v_mfma_f32_16x16x32_bf16 v[108:111], v[152:155], v[200:203], v[108:111]
	v_mfma_f32_16x16x32_bf16 v[104:107], v[160:163], v[200:203], v[104:107]
	v_mfma_f32_16x16x32_bf16 v[92:95], v[152:155], v[208:211], v[92:95]
	v_mfma_f32_16x16x32_bf16 v[88:91], v[160:163], v[208:211], v[88:91]
	v_mfma_f32_16x16x32_bf16 v[132:135], v[156:159], v[188:191], v[132:135]
	v_mfma_f32_16x16x32_bf16 v[128:131], v[164:167], v[188:191], v[128:131]
	v_mfma_f32_16x16x32_bf16 v[124:127], v[156:159], v[196:199], v[124:127]
	v_mfma_f32_16x16x32_bf16 v[120:123], v[164:167], v[196:199], v[120:123]
	v_mfma_f32_16x16x32_bf16 v[108:111], v[156:159], v[204:207], v[108:111]
	v_mfma_f32_16x16x32_bf16 v[104:107], v[164:167], v[204:207], v[104:107]
	v_mfma_f32_16x16x32_bf16 v[92:95], v[156:159], v[212:215], v[92:95]
	v_mfma_f32_16x16x32_bf16 v[88:91], v[164:167], v[212:215], v[88:91]
	v_mfma_f32_16x16x32_bf16 v[116:119], v[168:171], v[184:187], v[116:119]
	v_mfma_f32_16x16x32_bf16 v[112:115], v[176:179], v[184:187], v[112:115]
	v_mfma_f32_16x16x32_bf16 v[100:103], v[168:171], v[192:195], v[100:103]
	v_mfma_f32_16x16x32_bf16 v[96:99], v[176:179], v[192:195], v[96:99]
	v_mfma_f32_16x16x32_bf16 v[84:87], v[168:171], v[200:203], v[84:87]
	v_mfma_f32_16x16x32_bf16 v[80:83], v[176:179], v[200:203], v[80:83]
	v_mfma_f32_16x16x32_bf16 v[76:79], v[168:171], v[208:211], v[76:79]
	v_mfma_f32_16x16x32_bf16 v[72:75], v[176:179], v[208:211], v[72:75]
	v_mfma_f32_16x16x32_bf16 v[116:119], v[172:175], v[188:191], v[116:119]
	v_mfma_f32_16x16x32_bf16 v[112:115], v[180:183], v[188:191], v[112:115]
	v_mfma_f32_16x16x32_bf16 v[100:103], v[172:175], v[196:199], v[100:103]
	v_mfma_f32_16x16x32_bf16 v[96:99], v[180:183], v[196:199], v[96:99]
	v_mfma_f32_16x16x32_bf16 v[84:87], v[172:175], v[204:207], v[84:87]
	v_mfma_f32_16x16x32_bf16 v[80:83], v[180:183], v[204:207], v[80:83]
	v_mfma_f32_16x16x32_bf16 v[76:79], v[172:175], v[212:215], v[76:79]
	v_mfma_f32_16x16x32_bf16 v[72:75], v[180:183], v[212:215], v[72:75]
	s_barrier
	s_add_u32 s20, s18, 0x8000
	s_addc_u32 s21, s19, 0
	s_add_i32 s68, s68, s24
	s_mov_b32 m0, s68
	ds_read_b128 v[184:187], v150 offset:49152
	ds_read_b128 v[188:191], v150 offset:50176
	ds_read_b128 v[192:195], v150 offset:51200
	ds_read_b128 v[196:199], v150 offset:52224
	ds_read_b128 v[200:203], v150 offset:53248
	ds_read_b128 v[204:207], v150 offset:54272
	ds_read_b128 v[208:211], v150 offset:55296
	ds_read_b128 v[212:215], v150 offset:56320
	global_load_lds_dwordx4 v138, s[20:21]
	s_add_i32 m0, s68, 0x2000
	s_add_u32 s18, s18, 0xc000
	s_addc_u32 s19, s19, 0
	global_load_lds_dwordx4 v142, s[20:21]
	s_add_i32 s20, s69, s24
	s_mov_b32 m0, s20
	s_nop 0
	global_load_lds_dwordx4 v138, s[18:19]
	s_add_i32 m0, s20, 0x2000
	s_nop 0
	global_load_lds_dwordx4 v142, s[18:19]
	s_mov_b32 m0, s35
	s_nop 0
	global_load_lds_dwordx4 v136, s[16:17]
	s_mov_b32 m0, s70
	s_nop 0
	global_load_lds_dwordx4 v140, s[16:17]
	s_waitcnt vmcnt(8)
	s_waitcnt lgkmcnt(0)
	v_mfma_f32_16x16x32_bf16 v[68:71], v[152:155], v[184:187], v[68:71]
	v_mfma_f32_16x16x32_bf16 v[64:67], v[160:163], v[184:187], v[64:67]
	v_mfma_f32_16x16x32_bf16 v[60:63], v[152:155], v[192:195], v[60:63]
	v_mfma_f32_16x16x32_bf16 v[56:59], v[160:163], v[192:195], v[56:59]
	s_barrier
	v_mfma_f32_16x16x32_bf16 v[44:47], v[152:155], v[200:203], v[44:47]
	v_mfma_f32_16x16x32_bf16 v[40:43], v[160:163], v[200:203], v[40:43]
	v_mfma_f32_16x16x32_bf16 v[24:27], v[152:155], v[208:211], v[24:27]
	v_mfma_f32_16x16x32_bf16 v[20:23], v[160:163], v[208:211], v[20:23]
	v_mfma_f32_16x16x32_bf16 v[68:71], v[156:159], v[188:191], v[68:71]
	v_mfma_f32_16x16x32_bf16 v[64:67], v[164:167], v[188:191], v[64:67]
	v_mfma_f32_16x16x32_bf16 v[60:63], v[156:159], v[196:199], v[60:63]
	v_mfma_f32_16x16x32_bf16 v[56:59], v[164:167], v[196:199], v[56:59]
	v_mfma_f32_16x16x32_bf16 v[44:47], v[156:159], v[204:207], v[44:47]
	v_mfma_f32_16x16x32_bf16 v[40:43], v[164:167], v[204:207], v[40:43]
	v_mfma_f32_16x16x32_bf16 v[24:27], v[156:159], v[212:215], v[24:27]
	v_mfma_f32_16x16x32_bf16 v[20:23], v[164:167], v[212:215], v[20:23]
	v_mfma_f32_16x16x32_bf16 v[52:55], v[168:171], v[184:187], v[52:55]
	v_mfma_f32_16x16x32_bf16 v[48:51], v[176:179], v[184:187], v[48:51]
	v_mfma_f32_16x16x32_bf16 v[32:35], v[168:171], v[192:195], v[32:35]
	v_mfma_f32_16x16x32_bf16 v[28:31], v[176:179], v[192:195], v[28:31]
	v_mfma_f32_16x16x32_bf16 v[16:19], v[168:171], v[200:203], v[16:19]
	v_mfma_f32_16x16x32_bf16 v[12:15], v[176:179], v[200:203], v[12:15]
	v_mfma_f32_16x16x32_bf16 v[8:11], v[168:171], v[208:211], v[8:11]
	v_mfma_f32_16x16x32_bf16 v[4:7], v[176:179], v[208:211], v[4:7]
	v_mfma_f32_16x16x32_bf16 v[52:55], v[172:175], v[188:191], v[52:55]
	v_mfma_f32_16x16x32_bf16 v[48:51], v[180:183], v[188:191], v[48:51]
	v_mfma_f32_16x16x32_bf16 v[32:35], v[172:175], v[196:199], v[32:35]
	v_mfma_f32_16x16x32_bf16 v[28:31], v[180:183], v[196:199], v[28:31]
	v_mfma_f32_16x16x32_bf16 v[16:19], v[172:175], v[204:207], v[16:19]
	v_mfma_f32_16x16x32_bf16 v[12:15], v[180:183], v[204:207], v[12:15]
	v_mfma_f32_16x16x32_bf16 v[8:11], v[172:175], v[212:215], v[8:11]
	v_mfma_f32_16x16x32_bf16 v[4:7], v[180:183], v[212:215], v[4:7]
	s_barrier
	s_add_i32 s13, s13, 2
	s_add_u32 s10, s10, 0x10000
	s_addc_u32 s11, s11, 0
	s_add_u32 vcc_lo, vcc_lo, 0x10000
	s_addc_u32 vcc_hi, vcc_hi, 0
	s_cmpk_gt_u32 s13, 0x55
	s_cbranch_scc0 .LBB0_439
	s_setprio 0
	s_and_b64 vcc, exec, s[6:7]
	s_cbranch_vccz .LBB0_442
	s_barrier

; #define PG8_STAGE(bufoff, gbase, voff) do { _Pragma("unroll") for (int _i = 0; _i < 2; ++_i) \
;         __builtin_amdgcn_global_load_lds((const unsigned*)((const char*)(gbase) + (voff)[_i]), (PG8_LAS unsigned*)(lds + (bufoff) + ldsw + _i * 8192), 16, 0, 0); } while (0)
; #define PG8_LDA(dst, b, h) do { _Pragma("unroll") for (int m = 0; m < 4; ++m) _Pragma("unroll") for (int k = 0; k < 2; ++k) dst[m][k] = *(const PG8_LAS bf16x8*)(lds + PG8_SA(b, h) + aoff + m * 2048 + k * 1024); } while (0)
; #define PG8_LDB(dst, b, h) do { _Pragma("unroll") for (int n = 0; n < 2; ++n) _Pragma("unroll") for (int k = 0; k < 2; ++k) dst[n][k] = *(const PG8_LAS bf16x8*)(lds + PG8_SB(b, h) + boff + n * 2048 + k * 1024); } while (0)
; #define PG8_WAIT_V(n) asm volatile("s_waitcnt vmcnt(" #n ")" ::: "memory")
; #define PG8_WAIT_L(n) asm volatile("s_waitcnt lgkmcnt(" #n ")" ::: "memory")
; #define PG8_BAR __builtin_amdgcn_s_barrier()
; template <class Epi, class Sched, bool ALIGN_EPI = false, bool SP2 = false, bool ABLK = false, bool BBLK = false>
; __device__ __forceinline__ void gemm_phase(PG8_LAS unsigned char* lds, const Gemm g, const Sched& S, const Epi& E) {
;     ...
;         E.stage(cur, rs_area, wr, lane);
;         const char* nA = has_next ? (const char*)g.A + (size_t)nxt.pm * tstep : cA; const char* nB = has_next ? (const char*)g.Bt + (size_t)nxt.pn * tstep : cB;
;         for (int t = 0; t < nt; t += 2) {
;             const bool last = (t == nt - 2);
;             const char* a1 = cA + (size_t)(t + 1) * kstepA;
;             const char* a2 = last ? nA : cA + (size_t)(t + 2) * kstepA; const char* b2 = last ? nB : cB + (size_t)(t + 2) * kstepB;
;             const char* a3 = a2 + kstepA; const char* b3 = b2 + kstepB;
;             if (last && has_next) S.a_ready(nxt);
;             if constexpr (SP2) {
;             PG8_LDB(B0, 0, 0); PG8_LDB(B1, 0, 1); PG8_SCHED; PG8_LDA(At, 0, 0); PG8_STAGE(PG8_SA(1, 1), a1 + hstepA, voffA);
;             PG8_WAIT_V(8); PG8_WAIT_L(0); PG8_BAR; PG8_MMA(0, 0, At, B0); PG8_MMA(0, 1, At, B1); PG8_BAR; PG8_SCHED;
;     ...
; #pragma unroll
;         for (int a = 0; a < 2; ++a)
; #pragma unroll
;             for (int b = 0; b < 2; ++b)
; #pragma unroll
;                 for (int m = 0; m < 4; ++m)
; #pragma unroll
;                     for (int n = 0; n < 2; ++n) acc[a][b][m][n] = (f32x4){0.f, 0.f, 0.f, 0.f};
;         cur = nxt; cA = nA; cB = nB; ++ui;
.LBB0_915:
	s_lshl_b32 s18, s0, 8
	s_ashr_i32 s19, s18, 31
	s_mov_b32 m0, s63
	v_lshl_add_u64 v[4:5], s[18:19], 2, v[144:145]
	v_lshl_add_u64 v[6:7], v[4:5], 0, s[90:91]
	global_load_lds_dword v[4:5], off
	s_add_i32 m0, s63, 0x100
	s_mov_b32 s0, s1
	global_load_lds_dword v[6:7], off
	s_ashr_i32 s1, s1, 31
	s_lshl_b64 s[10:11], s[0:1], 20
	v_readlane_b32 s16, v252, 27
	v_readlane_b32 s17, v252, 28
	s_add_u32 s10, s16, s10
	s_addc_u32 s11, s17, s11
	s_and_b64 s[16:17], s[2:3], exec
	s_cselect_b32 s1, s11, s21
	s_cselect_b32 s19, s10, s20
	s_ashr_i32 s9, s8, 31
	s_lshl_b64 s[16:17], s[8:9], 20
	v_readlane_b32 s24, v254, 5
	v_readlane_b32 s25, v254, 6
	s_add_u32 s16, s24, s16
	s_addc_u32 s17, s25, s17
	s_and_b64 s[24:25], s[2:3], exec
	s_cselect_b32 s9, s17, s23
	s_cselect_b32 s65, s16, s22
	s_add_u32 s20, s20, 0xc000
	s_addc_u32 s21, s21, 0
	s_add_u32 s70, s22, 0x10000
	v_mov_b32_e32 v4, 0
	s_addc_u32 s71, s23, 0
	s_mov_b32 s13, -2
	v_readfirstlane_b32 s100, v0
	s_nop 3
	s_lshr_b32 s100, s100, 8
	s_cmp_eq_u32 s100, 0
	s_cbranch_scc1 .Lprio_done_2
	s_setprio 1
.Lprio_done_2:
	v_mov_b32_e32 v5, v4
	v_mov_b64_e32 v[6:7], 0
	v_mov_b64_e32 v[8:9], 0
	v_mov_b64_e32 v[10:11], 0
	v_mov_b64_e32 v[12:13], 0
	v_mov_b64_e32 v[14:15], 0
	v_mov_b64_e32 v[20:21], 0
	v_mov_b64_e32 v[22:23], 0
	v_mov_b64_e32 v[28:29], 0
	v_mov_b64_e32 v[30:31], 0
	v_mov_b64_e32 v[40:41], 0
	v_mov_b64_e32 v[42:43], 0
	v_mov_b64_e32 v[48:49], 0
	v_mov_b64_e32 v[50:51], 0
	v_mov_b64_e32 v[56:57], 0
	v_mov_b64_e32 v[58:59], 0
	v_mov_b64_e32 v[16:17], 0
	v_mov_b64_e32 v[18:19], 0
	v_mov_b64_e32 v[24:25], 0
	v_mov_b64_e32 v[26:27], 0
	v_mov_b64_e32 v[32:33], 0
	v_mov_b64_e32 v[34:35], 0
	v_mov_b64_e32 v[44:45], 0
	v_mov_b64_e32 v[46:47], 0
	v_mov_b64_e32 v[52:53], 0
	v_mov_b64_e32 v[54:55], 0
	v_mov_b64_e32 v[60:61], 0
	v_mov_b64_e32 v[62:63], 0
	v_mov_b64_e32 v[64:65], 0
	v_mov_b64_e32 v[66:67], 0
	v_mov_b64_e32 v[68:69], 0
	v_mov_b64_e32 v[70:71], 0
	v_mov_b64_e32 v[72:73], 0
	v_mov_b64_e32 v[74:75], 0
	v_mov_b64_e32 v[76:77], 0
	v_mov_b64_e32 v[78:79], 0
	v_mov_b64_e32 v[80:81], 0
	v_mov_b64_e32 v[82:83], 0
	v_mov_b64_e32 v[88:89], 0
	v_mov_b64_e32 v[90:91], 0
	v_mov_b64_e32 v[96:97], 0
	v_mov_b64_e32 v[98:99], 0
	v_mov_b64_e32 v[104:105], 0
	v_mov_b64_e32 v[106:107], 0
	v_mov_b64_e32 v[112:113], 0
	v_mov_b64_e32 v[114:115], 0
	v_mov_b64_e32 v[120:121], 0
	v_mov_b64_e32 v[122:123], 0
	v_mov_b64_e32 v[84:85], 0
	v_mov_b64_e32 v[86:87], 0
	v_mov_b64_e32 v[92:93], 0
	v_mov_b64_e32 v[94:95], 0
	v_mov_b64_e32 v[100:101], 0
	v_mov_b64_e32 v[102:103], 0
	v_mov_b64_e32 v[108:109], 0
	v_mov_b64_e32 v[110:111], 0
	v_mov_b64_e32 v[116:117], 0
	v_mov_b64_e32 v[118:119], 0
	v_mov_b64_e32 v[124:125], 0
	v_mov_b64_e32 v[126:127], 0
	v_mov_b64_e32 v[128:129], 0
	v_mov_b64_e32 v[130:131], 0
	v_mov_b64_e32 v[132:133], 0
	v_mov_b64_e32 v[134:135], 0
.LBB0_916:
	s_add_u32 s22, s20, 0x4000
	s_addc_u32 s23, s21, 0
	s_cmp_eq_u32 s13, 28
	s_cselect_b32 s26, s19, s22
	s_cselect_b32 s27, s1, s23
	s_cselect_b32 s24, s65, s70
	s_cselect_b32 s25, s9, s71
	s_add_u32 s22, s26, 0x8000
	s_addc_u32 s23, s27, 0
	s_add_i32 s68, 0, 0x10000
	v_add_u32_e32 v36, s68, v155
	s_add_i32 s77, 0, 0x14000
	ds_read_b128 v[150:153], v36
	ds_read_b128 v[158:161], v36 offset:1024
	ds_read_b128 v[162:165], v36 offset:2048
	ds_read_b128 v[166:169], v36 offset:3072
	v_add_u32_e32 v36, s77, v155
	ds_read_b128 v[170:173], v36
	ds_read_b128 v[174:177], v36 offset:1024
	ds_read_b128 v[178:181], v36 offset:2048
	ds_read_b128 v[182:185], v36 offset:3072
	s_add_i32 m0, s31, 0xc000
	ds_read_b128 v[186:189], v157
	ds_read_b128 v[190:193], v157 offset:1024
	ds_read_b128 v[194:197], v157 offset:2048
	ds_read_b128 v[198:201], v157 offset:3072
	ds_read_b128 v[202:205], v157 offset:4096
	ds_read_b128 v[206:209], v157 offset:5120
	ds_read_b128 v[210:213], v157 offset:6144
	ds_read_b128 v[214:217], v157 offset:7168
	global_load_lds_dwordx4 v146, s[20:21]
	s_add_i32 m0, s31, 0xe000
	s_nop 0
	global_load_lds_dwordx4 v148, s[20:21]
	s_waitcnt vmcnt(8)
	s_waitcnt lgkmcnt(0)
	v_mfma_f32_16x16x32_bf16 v[132:135], v[150:153], v[186:189], v[132:135]
	v_mfma_f32_16x16x32_bf16 v[128:131], v[162:165], v[186:189], v[128:131]
	v_mfma_f32_16x16x32_bf16 v[124:127], v[150:153], v[194:197], v[124:127]
	v_mfma_f32_16x16x32_bf16 v[116:119], v[162:165], v[194:197], v[116:119]
	s_barrier
	v_mfma_f32_16x16x32_bf16 v[108:111], v[150:153], v[202:205], v[108:111]
	v_mfma_f32_16x16x32_bf16 v[100:103], v[162:165], v[202:205], v[100:103]
	v_mfma_f32_16x16x32_bf16 v[92:95], v[150:153], v[210:213], v[92:95]
	v_mfma_f32_16x16x32_bf16 v[84:87], v[162:165], v[210:213], v[84:87]
	v_mfma_f32_16x16x32_bf16 v[132:135], v[158:161], v[190:193], v[132:135]
	v_mfma_f32_16x16x32_bf16 v[128:131], v[166:169], v[190:193], v[128:131]
	v_mfma_f32_16x16x32_bf16 v[124:127], v[158:161], v[198:201], v[124:127]
	v_mfma_f32_16x16x32_bf16 v[116:119], v[166:169], v[198:201], v[116:119]
	v_mfma_f32_16x16x32_bf16 v[108:111], v[158:161], v[206:209], v[108:111]
	v_mfma_f32_16x16x32_bf16 v[100:103], v[166:169], v[206:209], v[100:103]
	v_mfma_f32_16x16x32_bf16 v[92:95], v[158:161], v[214:217], v[92:95]
	v_mfma_f32_16x16x32_bf16 v[84:87], v[166:169], v[214:217], v[84:87]
	v_mfma_f32_16x16x32_bf16 v[120:123], v[170:173], v[186:189], v[120:123]
	v_mfma_f32_16x16x32_bf16 v[112:115], v[178:181], v[186:189], v[112:115]
	v_mfma_f32_16x16x32_bf16 v[104:107], v[170:173], v[194:197], v[104:107]
	v_mfma_f32_16x16x32_bf16 v[96:99], v[178:181], v[194:197], v[96:99]
	v_mfma_f32_16x16x32_bf16 v[88:91], v[170:173], v[202:205], v[88:91]
	v_mfma_f32_16x16x32_bf16 v[80:83], v[178:181], v[202:205], v[80:83]
	v_mfma_f32_16x16x32_bf16 v[76:79], v[170:173], v[210:213], v[76:79]
	v_mfma_f32_16x16x32_bf16 v[72:75], v[178:181], v[210:213], v[72:75]
	v_mfma_f32_16x16x32_bf16 v[120:123], v[174:177], v[190:193], v[120:123]
	v_mfma_f32_16x16x32_bf16 v[112:115], v[182:185], v[190:193], v[112:115]
	v_mfma_f32_16x16x32_bf16 v[104:107], v[174:177], v[198:201], v[104:107]
	v_mfma_f32_16x16x32_bf16 v[96:99], v[182:185], v[198:201], v[96:99]
	v_mfma_f32_16x16x32_bf16 v[88:91], v[174:177], v[206:209], v[88:91]
	v_mfma_f32_16x16x32_bf16 v[80:83], v[182:185], v[206:209], v[80:83]
	v_mfma_f32_16x16x32_bf16 v[76:79], v[174:177], v[214:217], v[76:79]
	v_mfma_f32_16x16x32_bf16 v[72:75], v[182:185], v[214:217], v[72:75]
	s_barrier
; #define PG8_STAGE(bufoff, gbase, voff) do { _Pragma("unroll") for (int _i = 0; _i < 2; ++_i) \
;         __builtin_amdgcn_global_load_lds((const unsigned*)((const char*)(gbase) + (voff)[_i]), (PG8_LAS unsigned*)(lds + (bufoff) + ldsw + _i * 8192), 16, 0, 0); } while (0)
; #define PG8_LDA(dst, b, h) do { _Pragma("unroll") for (int m = 0; m < 4; ++m) _Pragma("unroll") for (int k = 0; k < 2; ++k) dst[m][k] = *(const PG8_LAS bf16x8*)(lds + PG8_SA(b, h) + aoff + m * 2048 + k * 1024); } while (0)
; #define PG8_LDB(dst, b, h) do { _Pragma("unroll") for (int n = 0; n < 2; ++n) _Pragma("unroll") for (int k = 0; k < 2; ++k) dst[n][k] = *(const PG8_LAS bf16x8*)(lds + PG8_SB(b, h) + boff + n * 2048 + k * 1024); } while (0)
; #define PG8_MMA(ai, bj, At, Bt) do { __builtin_amdgcn_s_setprio(1); _Pragma("unroll") for (int m = 0; m < 4; ++m) _Pragma("unroll") for (int n = 0; n < 2; ++n) _Pragma("unroll") for (int k = 0; k < 2; ++k) \
;         acc[ai][bj][m][n] = __builtin_amdgcn_mfma_f32_16x16x32_bf16(Bt[n][k], At[m][k], acc[ai][bj][m][n], 0, 0, 0); __builtin_amdgcn_s_setprio(0); } while (0)
; #define PG8_WAIT_V(n) asm volatile("s_waitcnt vmcnt(" #n ")" ::: "memory")
; #define PG8_WAIT_L(n) asm volatile("s_waitcnt lgkmcnt(" #n ")" ::: "memory")
; #define PG8_BAR __builtin_amdgcn_s_barrier()
; #define PG8_SCHED __builtin_amdgcn_sched_barrier(0)
; template <class Epi, class Sched, bool ALIGN_EPI = false, bool SP2 = false, bool ABLK = false, bool BBLK = false>
; __device__ __forceinline__ void gemm_phase(PG8_LAS unsigned char* lds, const Gemm g, const Sched& S, const Epi& E) {
;     ...
;             PG8_WAIT_V(8); PG8_WAIT_L(0); PG8_BAR; PG8_MMA(0, 0, At, B0); PG8_MMA(0, 1, At, B1); PG8_BAR; PG8_SCHED;
;             PG8_LDA(At, 0, 1); PG8_STAGE(PG8_SB(0, 0), b2, voffB); PG8_STAGE(PG8_SB(0, 1), b2 + hstepB, voffB); PG8_STAGE(PG8_SA(0, 0), a2, voffA);
;             PG8_WAIT_V(8); PG8_WAIT_L(0); PG8_BAR; PG8_MMA(1, 0, At, B0); PG8_MMA(1, 1, At, B1); PG8_BAR; PG8_SCHED;
;             PG8_LDB(B0, 1, 0); PG8_LDB(B1, 1, 1); PG8_SCHED; PG8_LDA(At, 1, 0); PG8_STAGE(PG8_SA(0, 1), a2 + hstepA, voffA);
	s_add_i32 s68, s68, s29
	s_mov_b32 m0, s68
	ds_read_b128 v[186:189], v157 offset:16384
	ds_read_b128 v[190:193], v157 offset:17408
	ds_read_b128 v[194:197], v157 offset:18432
	ds_read_b128 v[198:201], v157 offset:19456
	ds_read_b128 v[202:205], v157 offset:20480
	ds_read_b128 v[206:209], v157 offset:21504
	ds_read_b128 v[210:213], v157 offset:22528
	ds_read_b128 v[214:217], v157 offset:23552
	global_load_lds_dwordx4 v140, s[24:25]
	s_add_i32 m0, s68, 0x2000
	s_add_u32 s68, s24, 0x4000
	s_addc_u32 s69, s25, 0
	s_add_i32 s77, s77, s29
	global_load_lds_dwordx4 v136, s[24:25]
	s_mov_b32 m0, s77
	s_nop 0
	global_load_lds_dwordx4 v140, s[68:69]
	s_add_i32 m0, s77, 0x2000
	s_nop 0
	global_load_lds_dwordx4 v136, s[68:69]
	s_mov_b32 m0, s31
	s_nop 0
	global_load_lds_dwordx4 v142, s[26:27]
	s_mov_b32 m0, s34
	s_nop 0
	global_load_lds_dwordx4 v138, s[26:27]
	s_waitcnt vmcnt(8)
	s_waitcnt lgkmcnt(0)
	v_mfma_f32_16x16x32_bf16 v[68:71], v[150:153], v[186:189], v[68:71]
	v_mfma_f32_16x16x32_bf16 v[64:67], v[162:165], v[186:189], v[64:67]
	v_mfma_f32_16x16x32_bf16 v[60:63], v[150:153], v[194:197], v[60:63]
	v_mfma_f32_16x16x32_bf16 v[52:55], v[162:165], v[194:197], v[52:55]
	s_barrier
	v_mfma_f32_16x16x32_bf16 v[44:47], v[150:153], v[202:205], v[44:47]
	v_mfma_f32_16x16x32_bf16 v[32:35], v[162:165], v[202:205], v[32:35]
	v_mfma_f32_16x16x32_bf16 v[24:27], v[150:153], v[210:213], v[24:27]
	v_mfma_f32_16x16x32_bf16 v[16:19], v[162:165], v[210:213], v[16:19]
	v_mfma_f32_16x16x32_bf16 v[68:71], v[158:161], v[190:193], v[68:71]
	v_mfma_f32_16x16x32_bf16 v[64:67], v[166:169], v[190:193], v[64:67]
	v_mfma_f32_16x16x32_bf16 v[60:63], v[158:161], v[198:201], v[60:63]
	v_mfma_f32_16x16x32_bf16 v[52:55], v[166:169], v[198:201], v[52:55]
	v_mfma_f32_16x16x32_bf16 v[44:47], v[158:161], v[206:209], v[44:47]
	v_mfma_f32_16x16x32_bf16 v[32:35], v[166:169], v[206:209], v[32:35]
	v_mfma_f32_16x16x32_bf16 v[24:27], v[158:161], v[214:217], v[24:27]
	v_mfma_f32_16x16x32_bf16 v[16:19], v[166:169], v[214:217], v[16:19]
	v_mfma_f32_16x16x32_bf16 v[56:59], v[170:173], v[186:189], v[56:59]
	v_mfma_f32_16x16x32_bf16 v[48:51], v[178:181], v[186:189], v[48:51]
	v_mfma_f32_16x16x32_bf16 v[40:43], v[170:173], v[194:197], v[40:43]
	v_mfma_f32_16x16x32_bf16 v[28:31], v[178:181], v[194:197], v[28:31]
	v_mfma_f32_16x16x32_bf16 v[20:23], v[170:173], v[202:205], v[20:23]
	v_mfma_f32_16x16x32_bf16 v[12:15], v[178:181], v[202:205], v[12:15]
	v_mfma_f32_16x16x32_bf16 v[8:11], v[170:173], v[210:213], v[8:11]
	v_mfma_f32_16x16x32_bf16 v[4:7], v[178:181], v[210:213], v[4:7]
	v_mfma_f32_16x16x32_bf16 v[56:59], v[174:177], v[190:193], v[56:59]
	v_mfma_f32_16x16x32_bf16 v[48:51], v[182:185], v[190:193], v[48:51]
	v_mfma_f32_16x16x32_bf16 v[40:43], v[174:177], v[198:201], v[40:43]
	v_mfma_f32_16x16x32_bf16 v[28:31], v[182:185], v[198:201], v[28:31]
	v_mfma_f32_16x16x32_bf16 v[20:23], v[174:177], v[206:209], v[20:23]
	v_mfma_f32_16x16x32_bf16 v[12:15], v[182:185], v[206:209], v[12:15]
	v_mfma_f32_16x16x32_bf16 v[8:11], v[174:177], v[214:217], v[8:11]
	v_mfma_f32_16x16x32_bf16 v[4:7], v[182:185], v[214:217], v[4:7]
	s_barrier
	s_add_i32 s68, 0, 0x18000
	v_add_u32_e32 v36, s68, v155
	s_add_i32 s69, 0, 0x1c000
	ds_read_b128 v[150:153], v36
	ds_read_b128 v[158:161], v36 offset:1024
	ds_read_b128 v[162:165], v36 offset:2048
	ds_read_b128 v[166:169], v36 offset:3072
	v_add_u32_e32 v36, s69, v155
	ds_read_b128 v[170:173], v36
	ds_read_b128 v[174:177], v36 offset:1024
	ds_read_b128 v[178:181], v36 offset:2048
	ds_read_b128 v[182:185], v36 offset:3072
	s_add_u32 s26, s26, 0x4000
	s_addc_u32 s27, s27, 0
	s_mov_b32 m0, s35
	ds_read_b128 v[186:189], v157 offset:32768
	ds_read_b128 v[190:193], v157 offset:33792
	ds_read_b128 v[194:197], v157 offset:34816
	ds_read_b128 v[198:201], v157 offset:35840
	ds_read_b128 v[202:205], v157 offset:36864
	ds_read_b128 v[206:209], v157 offset:37888
	ds_read_b128 v[210:213], v157 offset:38912
	ds_read_b128 v[214:217], v157 offset:39936
	global_load_lds_dwordx4 v142, s[26:27]
	s_mov_b32 m0, s36
	s_nop 0
	global_load_lds_dwordx4 v138, s[26:27]
	s_waitcnt vmcnt(8)
	s_waitcnt lgkmcnt(0)
	v_mfma_f32_16x16x32_bf16 v[132:135], v[150:153], v[186:189], v[132:135]
	v_mfma_f32_16x16x32_bf16 v[128:131], v[162:165], v[186:189], v[128:131]
	v_mfma_f32_16x16x32_bf16 v[124:127], v[150:153], v[194:197], v[124:127]
	v_mfma_f32_16x16x32_bf16 v[116:119], v[162:165], v[194:197], v[116:119]
	s_barrier
; #define PG8_STAGE(bufoff, gbase, voff) do { _Pragma("unroll") for (int _i = 0; _i < 2; ++_i) \
;         __builtin_amdgcn_global_load_lds((const unsigned*)((const char*)(gbase) + (voff)[_i]), (PG8_LAS unsigned*)(lds + (bufoff) + ldsw + _i * 8192), 16, 0, 0); } while (0)
; #define PG8_LDA(dst, b, h) do { _Pragma("unroll") for (int m = 0; m < 4; ++m) _Pragma("unroll") for (int k = 0; k < 2; ++k) dst[m][k] = *(const PG8_LAS bf16x8*)(lds + PG8_SA(b, h) + aoff + m * 2048 + k * 1024); } while (0)
; #define PG8_MMA(ai, bj, At, Bt) do { __builtin_amdgcn_s_setprio(1); _Pragma("unroll") for (int m = 0; m < 4; ++m) _Pragma("unroll") for (int n = 0; n < 2; ++n) _Pragma("unroll") for (int k = 0; k < 2; ++k) \
;         acc[ai][bj][m][n] = __builtin_amdgcn_mfma_f32_16x16x32_bf16(Bt[n][k], At[m][k], acc[ai][bj][m][n], 0, 0, 0); __builtin_amdgcn_s_setprio(0); } while (0)
; #define PG8_WAIT_V(n) asm volatile("s_waitcnt vmcnt(" #n ")" ::: "memory")
; #define PG8_WAIT_L(n) asm volatile("s_waitcnt lgkmcnt(" #n ")" ::: "memory")
; #define PG8_BAR __builtin_amdgcn_s_barrier()
; #define PG8_SCHED __builtin_amdgcn_sched_barrier(0)
; template <class Epi, class Sched, bool ALIGN_EPI = false, bool SP2 = false, bool ABLK = false, bool BBLK = false>
; __device__ __forceinline__ void gemm_phase(PG8_LAS unsigned char* lds, const Gemm g, const Sched& S, const Epi& E) {
;     ...
;             PG8_WAIT_V(8); PG8_WAIT_L(0); PG8_BAR; PG8_MMA(0, 0, At, B0); PG8_MMA(0, 1, At, B1); PG8_BAR; PG8_SCHED;
;             PG8_LDA(At, 1, 1); PG8_STAGE(PG8_SB(1, 0), b3, voffB); PG8_STAGE(PG8_SB(1, 1), b3 + hstepB, voffB); PG8_STAGE(PG8_SA(1, 0), a3, voffA);
;             PG8_WAIT_V(8); PG8_WAIT_L(0); PG8_BAR; PG8_MMA(1, 0, At, B0); PG8_MMA(1, 1, At, B1); PG8_BAR; PG8_SCHED;
;     ...
;         if constexpr (ALIGN_EPI) { if (wr == 0) PG8_BAR; }
	v_mfma_f32_16x16x32_bf16 v[108:111], v[150:153], v[202:205], v[108:111]
	v_mfma_f32_16x16x32_bf16 v[100:103], v[162:165], v[202:205], v[100:103]
	v_mfma_f32_16x16x32_bf16 v[92:95], v[150:153], v[210:213], v[92:95]
	v_mfma_f32_16x16x32_bf16 v[84:87], v[162:165], v[210:213], v[84:87]
	v_mfma_f32_16x16x32_bf16 v[132:135], v[158:161], v[190:193], v[132:135]
	v_mfma_f32_16x16x32_bf16 v[128:131], v[166:169], v[190:193], v[128:131]
	v_mfma_f32_16x16x32_bf16 v[124:127], v[158:161], v[198:201], v[124:127]
	v_mfma_f32_16x16x32_bf16 v[116:119], v[166:169], v[198:201], v[116:119]
	v_mfma_f32_16x16x32_bf16 v[108:111], v[158:161], v[206:209], v[108:111]
	v_mfma_f32_16x16x32_bf16 v[100:103], v[166:169], v[206:209], v[100:103]
	v_mfma_f32_16x16x32_bf16 v[92:95], v[158:161], v[214:217], v[92:95]
	v_mfma_f32_16x16x32_bf16 v[84:87], v[166:169], v[214:217], v[84:87]
	v_mfma_f32_16x16x32_bf16 v[120:123], v[170:173], v[186:189], v[120:123]
	v_mfma_f32_16x16x32_bf16 v[112:115], v[178:181], v[186:189], v[112:115]
	v_mfma_f32_16x16x32_bf16 v[104:107], v[170:173], v[194:197], v[104:107]
	v_mfma_f32_16x16x32_bf16 v[96:99], v[178:181], v[194:197], v[96:99]
	v_mfma_f32_16x16x32_bf16 v[88:91], v[170:173], v[202:205], v[88:91]
	v_mfma_f32_16x16x32_bf16 v[80:83], v[178:181], v[202:205], v[80:83]
	v_mfma_f32_16x16x32_bf16 v[76:79], v[170:173], v[210:213], v[76:79]
	v_mfma_f32_16x16x32_bf16 v[72:75], v[178:181], v[210:213], v[72:75]
	v_mfma_f32_16x16x32_bf16 v[120:123], v[174:177], v[190:193], v[120:123]
	v_mfma_f32_16x16x32_bf16 v[112:115], v[182:185], v[190:193], v[112:115]
	v_mfma_f32_16x16x32_bf16 v[104:107], v[174:177], v[198:201], v[104:107]
	v_mfma_f32_16x16x32_bf16 v[96:99], v[182:185], v[198:201], v[96:99]
	v_mfma_f32_16x16x32_bf16 v[88:91], v[174:177], v[206:209], v[88:91]
	v_mfma_f32_16x16x32_bf16 v[80:83], v[182:185], v[206:209], v[80:83]
	v_mfma_f32_16x16x32_bf16 v[76:79], v[174:177], v[214:217], v[76:79]
	v_mfma_f32_16x16x32_bf16 v[72:75], v[182:185], v[214:217], v[72:75]
	s_barrier
	s_add_u32 s26, s24, 0x8000
	s_addc_u32 s27, s25, 0
	s_add_i32 s68, s68, s29
	s_mov_b32 m0, s68
	ds_read_b128 v[186:189], v157 offset:49152
	ds_read_b128 v[190:193], v157 offset:50176
	ds_read_b128 v[194:197], v157 offset:51200
	ds_read_b128 v[198:201], v157 offset:52224
	ds_read_b128 v[202:205], v157 offset:53248
	ds_read_b128 v[206:209], v157 offset:54272
	ds_read_b128 v[210:213], v157 offset:55296
	ds_read_b128 v[214:217], v157 offset:56320
	global_load_lds_dwordx4 v140, s[26:27]
	s_add_i32 m0, s68, 0x2000
	s_add_u32 s24, s24, 0xc000
	s_addc_u32 s25, s25, 0
	global_load_lds_dwordx4 v136, s[26:27]
	s_add_i32 s26, s69, s29
	s_mov_b32 m0, s26
	s_nop 0
	global_load_lds_dwordx4 v140, s[24:25]
	s_add_i32 m0, s26, 0x2000
	s_nop 0
	global_load_lds_dwordx4 v136, s[24:25]
	s_mov_b32 m0, s37
	s_nop 0
	global_load_lds_dwordx4 v142, s[22:23]
	s_mov_b32 m0, s62
	s_nop 0
	global_load_lds_dwordx4 v138, s[22:23]
	s_waitcnt vmcnt(8)
	s_waitcnt lgkmcnt(0)
	v_mfma_f32_16x16x32_bf16 v[68:71], v[150:153], v[186:189], v[68:71]
	v_mfma_f32_16x16x32_bf16 v[64:67], v[162:165], v[186:189], v[64:67]
	v_mfma_f32_16x16x32_bf16 v[60:63], v[150:153], v[194:197], v[60:63]
	v_mfma_f32_16x16x32_bf16 v[52:55], v[162:165], v[194:197], v[52:55]
	s_barrier
	v_mfma_f32_16x16x32_bf16 v[44:47], v[150:153], v[202:205], v[44:47]
	v_mfma_f32_16x16x32_bf16 v[32:35], v[162:165], v[202:205], v[32:35]
	v_mfma_f32_16x16x32_bf16 v[24:27], v[150:153], v[210:213], v[24:27]
	v_mfma_f32_16x16x32_bf16 v[16:19], v[162:165], v[210:213], v[16:19]
	v_mfma_f32_16x16x32_bf16 v[68:71], v[158:161], v[190:193], v[68:71]
	v_mfma_f32_16x16x32_bf16 v[64:67], v[166:169], v[190:193], v[64:67]
	v_mfma_f32_16x16x32_bf16 v[60:63], v[158:161], v[198:201], v[60:63]
	v_mfma_f32_16x16x32_bf16 v[52:55], v[166:169], v[198:201], v[52:55]
	v_mfma_f32_16x16x32_bf16 v[44:47], v[158:161], v[206:209], v[44:47]
	v_mfma_f32_16x16x32_bf16 v[32:35], v[166:169], v[206:209], v[32:35]
	v_mfma_f32_16x16x32_bf16 v[24:27], v[158:161], v[214:217], v[24:27]
	v_mfma_f32_16x16x32_bf16 v[16:19], v[166:169], v[214:217], v[16:19]
	v_mfma_f32_16x16x32_bf16 v[56:59], v[170:173], v[186:189], v[56:59]
	v_mfma_f32_16x16x32_bf16 v[48:51], v[178:181], v[186:189], v[48:51]
	v_mfma_f32_16x16x32_bf16 v[40:43], v[170:173], v[194:197], v[40:43]
	v_mfma_f32_16x16x32_bf16 v[28:31], v[178:181], v[194:197], v[28:31]
	v_mfma_f32_16x16x32_bf16 v[20:23], v[170:173], v[202:205], v[20:23]
	v_mfma_f32_16x16x32_bf16 v[12:15], v[178:181], v[202:205], v[12:15]
	v_mfma_f32_16x16x32_bf16 v[8:11], v[170:173], v[210:213], v[8:11]
	v_mfma_f32_16x16x32_bf16 v[4:7], v[178:181], v[210:213], v[4:7]
	v_mfma_f32_16x16x32_bf16 v[56:59], v[174:177], v[190:193], v[56:59]
	v_mfma_f32_16x16x32_bf16 v[48:51], v[182:185], v[190:193], v[48:51]
	v_mfma_f32_16x16x32_bf16 v[40:43], v[174:177], v[198:201], v[40:43]
	v_mfma_f32_16x16x32_bf16 v[28:31], v[182:185], v[198:201], v[28:31]
	v_mfma_f32_16x16x32_bf16 v[20:23], v[174:177], v[206:209], v[20:23]
	v_mfma_f32_16x16x32_bf16 v[12:15], v[182:185], v[206:209], v[12:15]
	v_mfma_f32_16x16x32_bf16 v[8:11], v[174:177], v[214:217], v[8:11]
	v_mfma_f32_16x16x32_bf16 v[4:7], v[182:185], v[214:217], v[4:7]
	s_barrier
	s_add_i32 s13, s13, 2
	s_add_u32 s20, s20, 0x10000
	s_addc_u32 s21, s21, 0
	s_add_u32 s70, s70, 0x10000
	s_addc_u32 s71, s71, 0
	s_cmp_gt_u32 s13, 29
	s_cbranch_scc0 .LBB0_916
	s_setprio 0
	s_and_b64 vcc, exec, s[6:7]
	s_cbranch_vccz .LBB0_919
	s_barrier

; template <class Epi, class Sched, bool ALIGN_EPI = false, bool SP2 = false, bool ABLK = false, bool BBLK = false>
; __device__ __forceinline__ void gemm_phase(PG8_LAS unsigned char* lds, const Gemm g, const Sched& S, const Epi& E) {
;     ...
;         const char* nA = has_next ? (const char*)g.A + (size_t)nxt.pm * tstep : cA; const char* nB = has_next ? (const char*)g.Bt + (size_t)nxt.pn * tstep : cB;
;         for (int t = 0; t < nt; t += 2) {
;             const bool last = (t == nt - 2);
;             const char* a1 = cA + (size_t)(t + 1) * kstepA;
;             const char* a2 = last ? nA : cA + (size_t)(t + 2) * kstepA; const char* b2 = last ? nB : cB + (size_t)(t + 2) * kstepB;
;             const char* a3 = a2 + kstepA; const char* b3 = b2 + kstepB;
.LBB0_2110:
	s_ashr_i32 s17, s16, 31
	s_lshl_b64 s[12:13], s[16:17], 20
	s_add_u32 s18, s72, s12
	s_addc_u32 s19, s73, s13
	s_and_b64 s[12:13], s[4:5], exec
	s_cselect_b32 s12, s19, s23
	s_cselect_b32 s17, s18, s22
	s_ashr_i32 s11, s10, 31
	s_lshl_b64 s[20:21], s[10:11], 20
	v_readlane_b32 s26, v254, 3
	v_readlane_b32 s27, v254, 4
	s_add_u32 s20, s26, s20
	s_addc_u32 s21, s27, s21
	s_and_b64 s[26:27], s[4:5], exec
	s_cselect_b32 s11, s21, s25
	s_cselect_b32 s77, s20, s24
	s_add_u32 s22, s22, 0xc000
	s_addc_u32 s23, s23, 0
	s_add_u32 s82, s24, 0x10000
	v_mov_b32_e32 v4, 0
	s_addc_u32 vcc_lo, s25, 0
	s_mov_b32 s13, -2
	v_readfirstlane_b32 s100, v0
	s_nop 3
	s_lshr_b32 s100, s100, 8
	s_cmp_eq_u32 s100, 0
	s_cbranch_scc1 .Lprio_done_3
	s_setprio 1

; #define PG8_STAGE(bufoff, gbase, voff) do { _Pragma("unroll") for (int _i = 0; _i < 2; ++_i) \
;         __builtin_amdgcn_global_load_lds((const unsigned*)((const char*)(gbase) + (voff)[_i]), (PG8_LAS unsigned*)(lds + (bufoff) + ldsw + _i * 8192), 16, 0, 0); } while (0)
; #define PG8_LDA(dst, b, h) do { _Pragma("unroll") for (int m = 0; m < 4; ++m) _Pragma("unroll") for (int k = 0; k < 2; ++k) dst[m][k] = *(const PG8_LAS bf16x8*)(lds + PG8_SA(b, h) + aoff + m * 2048 + k * 1024); } while (0)
; #define PG8_LDB(dst, b, h) do { _Pragma("unroll") for (int n = 0; n < 2; ++n) _Pragma("unroll") for (int k = 0; k < 2; ++k) dst[n][k] = *(const PG8_LAS bf16x8*)(lds + PG8_SB(b, h) + boff + n * 2048 + k * 1024); } while (0)
; #define PG8_MMA(ai, bj, At, Bt) do { __builtin_amdgcn_s_setprio(1); _Pragma("unroll") for (int m = 0; m < 4; ++m) _Pragma("unroll") for (int n = 0; n < 2; ++n) _Pragma("unroll") for (int k = 0; k < 2; ++k) \
;         acc[ai][bj][m][n] = __builtin_amdgcn_mfma_f32_16x16x32_bf16(Bt[n][k], At[m][k], acc[ai][bj][m][n], 0, 0, 0); __builtin_amdgcn_s_setprio(0); } while (0)
; #define PG8_WAIT_V(n) asm volatile("s_waitcnt vmcnt(" #n ")" ::: "memory")
; #define PG8_WAIT_L(n) asm volatile("s_waitcnt lgkmcnt(" #n ")" ::: "memory")
; #define PG8_BAR __builtin_amdgcn_s_barrier()
; #define PG8_SCHED __builtin_amdgcn_sched_barrier(0)
; template <class Epi, class Sched, bool ALIGN_EPI = false, bool SP2 = false, bool ABLK = false, bool BBLK = false>
; __device__ __forceinline__ void gemm_phase(PG8_LAS unsigned char* lds, const Gemm g, const Sched& S, const Epi& E) {
;     ...
;             PG8_LDB(B0, 0, 0); PG8_LDB(B1, 0, 1); PG8_SCHED; PG8_LDA(At, 0, 0); PG8_STAGE(PG8_SA(1, 1), a1 + hstepA, voffA);
;             PG8_WAIT_V(8); PG8_WAIT_L(0); PG8_BAR; PG8_MMA(0, 0, At, B0); PG8_MMA(0, 1, At, B1); PG8_BAR; PG8_SCHED;
;             PG8_LDA(At, 0, 1); PG8_STAGE(PG8_SB(0, 0), b2, voffB); PG8_STAGE(PG8_SB(0, 1), b2 + hstepB, voffB); PG8_STAGE(PG8_SA(0, 0), a2, voffA);
;             PG8_WAIT_V(8); PG8_WAIT_L(0); PG8_BAR; PG8_MMA(1, 0, At, B0); PG8_MMA(1, 1, At, B1); PG8_BAR; PG8_SCHED;
.LBB0_2111:
	s_add_u32 s24, s22, 0x4000
	s_addc_u32 s25, s23, 0
	s_cmp_eq_u32 s13, 28
	s_cselect_b32 s28, s17, s24
	s_cselect_b32 s29, s12, s25
	s_cselect_b32 s26, s77, s82
	s_cselect_b32 s27, s11, vcc_lo
	s_add_u32 s24, s28, 0x8000
	s_addc_u32 s25, s29, 0
	s_add_i32 s68, 0, 0x10000
	v_add_u32_e32 v151, s68, v148
	s_add_i32 s88, 0, 0x14000
	ds_read_b128 v[36:39], v151
	ds_read_b128 v[152:155], v151 offset:1024
	ds_read_b128 v[156:159], v151 offset:2048
	ds_read_b128 v[160:163], v151 offset:3072
	v_add_u32_e32 v151, s88, v148
	ds_read_b128 v[164:167], v151
	ds_read_b128 v[168:171], v151 offset:1024
	ds_read_b128 v[172:175], v151 offset:2048
	ds_read_b128 v[176:179], v151 offset:3072
	s_add_i32 m0, s9, 0xc000
	ds_read_b128 v[180:183], v150
	ds_read_b128 v[184:187], v150 offset:1024
	ds_read_b128 v[188:191], v150 offset:2048
	ds_read_b128 v[192:195], v150 offset:3072
	ds_read_b128 v[196:199], v150 offset:4096
	ds_read_b128 v[200:203], v150 offset:5120
	ds_read_b128 v[204:207], v150 offset:6144
	ds_read_b128 v[208:211], v150 offset:7168
	global_load_lds_dwordx4 v144, s[22:23]
	s_add_i32 m0, s9, 0xe000
	s_nop 0
	global_load_lds_dwordx4 v146, s[22:23]
	s_waitcnt vmcnt(8)
	s_waitcnt lgkmcnt(0)
	v_mfma_f32_16x16x32_bf16 v[132:135], v[36:39], v[180:183], v[132:135]
	v_mfma_f32_16x16x32_bf16 v[128:131], v[156:159], v[180:183], v[128:131]
	v_mfma_f32_16x16x32_bf16 v[124:127], v[36:39], v[188:191], v[124:127]
	v_mfma_f32_16x16x32_bf16 v[120:123], v[156:159], v[188:191], v[120:123]
	s_barrier
	v_mfma_f32_16x16x32_bf16 v[108:111], v[36:39], v[196:199], v[108:111]
	v_mfma_f32_16x16x32_bf16 v[104:107], v[156:159], v[196:199], v[104:107]
	v_mfma_f32_16x16x32_bf16 v[92:95], v[36:39], v[204:207], v[92:95]
	v_mfma_f32_16x16x32_bf16 v[88:91], v[156:159], v[204:207], v[88:91]
	v_mfma_f32_16x16x32_bf16 v[132:135], v[152:155], v[184:187], v[132:135]
	v_mfma_f32_16x16x32_bf16 v[128:131], v[160:163], v[184:187], v[128:131]
	v_mfma_f32_16x16x32_bf16 v[124:127], v[152:155], v[192:195], v[124:127]
	v_mfma_f32_16x16x32_bf16 v[120:123], v[160:163], v[192:195], v[120:123]
	v_mfma_f32_16x16x32_bf16 v[108:111], v[152:155], v[200:203], v[108:111]
	v_mfma_f32_16x16x32_bf16 v[104:107], v[160:163], v[200:203], v[104:107]
	v_mfma_f32_16x16x32_bf16 v[92:95], v[152:155], v[208:211], v[92:95]
	v_mfma_f32_16x16x32_bf16 v[88:91], v[160:163], v[208:211], v[88:91]
	v_mfma_f32_16x16x32_bf16 v[116:119], v[164:167], v[180:183], v[116:119]
	v_mfma_f32_16x16x32_bf16 v[112:115], v[172:175], v[180:183], v[112:115]
	v_mfma_f32_16x16x32_bf16 v[100:103], v[164:167], v[188:191], v[100:103]
	v_mfma_f32_16x16x32_bf16 v[96:99], v[172:175], v[188:191], v[96:99]
	v_mfma_f32_16x16x32_bf16 v[84:87], v[164:167], v[196:199], v[84:87]
	v_mfma_f32_16x16x32_bf16 v[80:83], v[172:175], v[196:199], v[80:83]
	v_mfma_f32_16x16x32_bf16 v[76:79], v[164:167], v[204:207], v[76:79]
	v_mfma_f32_16x16x32_bf16 v[72:75], v[172:175], v[204:207], v[72:75]
	v_mfma_f32_16x16x32_bf16 v[116:119], v[168:171], v[184:187], v[116:119]
	v_mfma_f32_16x16x32_bf16 v[112:115], v[176:179], v[184:187], v[112:115]
	v_mfma_f32_16x16x32_bf16 v[100:103], v[168:171], v[192:195], v[100:103]
	v_mfma_f32_16x16x32_bf16 v[96:99], v[176:179], v[192:195], v[96:99]
	v_mfma_f32_16x16x32_bf16 v[84:87], v[168:171], v[200:203], v[84:87]
	v_mfma_f32_16x16x32_bf16 v[80:83], v[176:179], v[200:203], v[80:83]
	v_mfma_f32_16x16x32_bf16 v[76:79], v[168:171], v[208:211], v[76:79]
	v_mfma_f32_16x16x32_bf16 v[72:75], v[176:179], v[208:211], v[72:75]
	s_barrier
	s_add_i32 s68, s68, s34
	s_mov_b32 m0, s68
	ds_read_b128 v[180:183], v150 offset:16384
	ds_read_b128 v[184:187], v150 offset:17408
	ds_read_b128 v[188:191], v150 offset:18432
	ds_read_b128 v[192:195], v150 offset:19456
	ds_read_b128 v[196:199], v150 offset:20480
	ds_read_b128 v[200:203], v150 offset:21504
	ds_read_b128 v[204:207], v150 offset:22528
	ds_read_b128 v[208:211], v150 offset:23552
	global_load_lds_dwordx4 v138, s[26:27]
	s_add_i32 m0, s68, 0x2000
	s_add_u32 s68, s26, 0x4000
	s_addc_u32 s69, s27, 0
	s_add_i32 s88, s88, s34
	global_load_lds_dwordx4 v142, s[26:27]
	s_mov_b32 m0, s88
	s_nop 0
	global_load_lds_dwordx4 v138, s[68:69]
	s_add_i32 m0, s88, 0x2000
	s_nop 0
	global_load_lds_dwordx4 v142, s[68:69]
	s_mov_b32 m0, s9
	s_nop 0
	global_load_lds_dwordx4 v136, s[28:29]
	s_mov_b32 m0, s35
	s_nop 0
	global_load_lds_dwordx4 v140, s[28:29]
	s_waitcnt vmcnt(8)
	s_waitcnt lgkmcnt(0)
	v_mfma_f32_16x16x32_bf16 v[68:71], v[36:39], v[180:183], v[68:71]
	v_mfma_f32_16x16x32_bf16 v[64:67], v[156:159], v[180:183], v[64:67]
	v_mfma_f32_16x16x32_bf16 v[60:63], v[36:39], v[188:191], v[60:63]
	v_mfma_f32_16x16x32_bf16 v[56:59], v[156:159], v[188:191], v[56:59]
	s_barrier
; #define PG8_STAGE(bufoff, gbase, voff) do { _Pragma("unroll") for (int _i = 0; _i < 2; ++_i) \
;         __builtin_amdgcn_global_load_lds((const unsigned*)((const char*)(gbase) + (voff)[_i]), (PG8_LAS unsigned*)(lds + (bufoff) + ldsw + _i * 8192), 16, 0, 0); } while (0)
; #define PG8_LDA(dst, b, h) do { _Pragma("unroll") for (int m = 0; m < 4; ++m) _Pragma("unroll") for (int k = 0; k < 2; ++k) dst[m][k] = *(const PG8_LAS bf16x8*)(lds + PG8_SA(b, h) + aoff + m * 2048 + k * 1024); } while (0)
; #define PG8_LDB(dst, b, h) do { _Pragma("unroll") for (int n = 0; n < 2; ++n) _Pragma("unroll") for (int k = 0; k < 2; ++k) dst[n][k] = *(const PG8_LAS bf16x8*)(lds + PG8_SB(b, h) + boff + n * 2048 + k * 1024); } while (0)
; #define PG8_MMA(ai, bj, At, Bt) do { __builtin_amdgcn_s_setprio(1); _Pragma("unroll") for (int m = 0; m < 4; ++m) _Pragma("unroll") for (int n = 0; n < 2; ++n) _Pragma("unroll") for (int k = 0; k < 2; ++k) \
;         acc[ai][bj][m][n] = __builtin_amdgcn_mfma_f32_16x16x32_bf16(Bt[n][k], At[m][k], acc[ai][bj][m][n], 0, 0, 0); __builtin_amdgcn_s_setprio(0); } while (0)
; #define PG8_WAIT_V(n) asm volatile("s_waitcnt vmcnt(" #n ")" ::: "memory")
; #define PG8_WAIT_L(n) asm volatile("s_waitcnt lgkmcnt(" #n ")" ::: "memory")
; #define PG8_BAR __builtin_amdgcn_s_barrier()
; #define PG8_SCHED __builtin_amdgcn_sched_barrier(0)
; template <class Epi, class Sched, bool ALIGN_EPI = false, bool SP2 = false, bool ABLK = false, bool BBLK = false>
; __device__ __forceinline__ void gemm_phase(PG8_LAS unsigned char* lds, const Gemm g, const Sched& S, const Epi& E) {
;     ...
;             PG8_WAIT_V(8); PG8_WAIT_L(0); PG8_BAR; PG8_MMA(1, 0, At, B0); PG8_MMA(1, 1, At, B1); PG8_BAR; PG8_SCHED;
;             PG8_LDB(B0, 1, 0); PG8_LDB(B1, 1, 1); PG8_SCHED; PG8_LDA(At, 1, 0); PG8_STAGE(PG8_SA(0, 1), a2 + hstepA, voffA);
;             PG8_WAIT_V(8); PG8_WAIT_L(0); PG8_BAR; PG8_MMA(0, 0, At, B0); PG8_MMA(0, 1, At, B1); PG8_BAR; PG8_SCHED;
	v_mfma_f32_16x16x32_bf16 v[44:47], v[36:39], v[196:199], v[44:47]
	v_mfma_f32_16x16x32_bf16 v[40:43], v[156:159], v[196:199], v[40:43]
	v_mfma_f32_16x16x32_bf16 v[24:27], v[36:39], v[204:207], v[24:27]
	v_mfma_f32_16x16x32_bf16 v[20:23], v[156:159], v[204:207], v[20:23]
	v_mfma_f32_16x16x32_bf16 v[68:71], v[152:155], v[184:187], v[68:71]
	v_mfma_f32_16x16x32_bf16 v[64:67], v[160:163], v[184:187], v[64:67]
	v_mfma_f32_16x16x32_bf16 v[60:63], v[152:155], v[192:195], v[60:63]
	v_mfma_f32_16x16x32_bf16 v[56:59], v[160:163], v[192:195], v[56:59]
	v_mfma_f32_16x16x32_bf16 v[44:47], v[152:155], v[200:203], v[44:47]
	v_mfma_f32_16x16x32_bf16 v[40:43], v[160:163], v[200:203], v[40:43]
	v_mfma_f32_16x16x32_bf16 v[24:27], v[152:155], v[208:211], v[24:27]
	v_mfma_f32_16x16x32_bf16 v[20:23], v[160:163], v[208:211], v[20:23]
	v_mfma_f32_16x16x32_bf16 v[48:51], v[172:175], v[180:183], v[48:51]
	v_mfma_f32_16x16x32_bf16 v[32:35], v[164:167], v[188:191], v[32:35]
	v_mfma_f32_16x16x32_bf16 v[28:31], v[172:175], v[188:191], v[28:31]
	v_mfma_f32_16x16x32_bf16 v[16:19], v[164:167], v[196:199], v[16:19]
	v_mfma_f32_16x16x32_bf16 v[12:15], v[172:175], v[196:199], v[12:15]
	v_mfma_f32_16x16x32_bf16 v[8:11], v[164:167], v[204:207], v[8:11]
	v_mfma_f32_16x16x32_bf16 v[4:7], v[172:175], v[204:207], v[4:7]
	v_mfma_f32_16x16x32_bf16 v[36:39], v[164:167], v[180:183], v[52:55]
	v_mfma_f32_16x16x32_bf16 v[48:51], v[176:179], v[184:187], v[48:51]
	v_mfma_f32_16x16x32_bf16 v[32:35], v[168:171], v[192:195], v[32:35]
	v_mfma_f32_16x16x32_bf16 v[28:31], v[176:179], v[192:195], v[28:31]
	v_mfma_f32_16x16x32_bf16 v[16:19], v[168:171], v[200:203], v[16:19]
	v_mfma_f32_16x16x32_bf16 v[12:15], v[176:179], v[200:203], v[12:15]
	v_mfma_f32_16x16x32_bf16 v[8:11], v[168:171], v[208:211], v[8:11]
	v_mfma_f32_16x16x32_bf16 v[4:7], v[176:179], v[208:211], v[4:7]
	v_mfma_f32_16x16x32_bf16 v[36:39], v[168:171], v[184:187], v[36:39]
	s_barrier
	s_add_i32 s68, 0, 0x18000
	v_add_u32_e32 v151, s68, v148
	s_add_i32 s69, 0, 0x1c000
	ds_read_b128 v[52:55], v151
	ds_read_b128 v[152:155], v151 offset:1024
	ds_read_b128 v[156:159], v151 offset:2048
	ds_read_b128 v[160:163], v151 offset:3072
	v_add_u32_e32 v151, s69, v148
	ds_read_b128 v[164:167], v151
	ds_read_b128 v[168:171], v151 offset:1024
	ds_read_b128 v[172:175], v151 offset:2048
	ds_read_b128 v[176:179], v151 offset:3072
	s_add_u32 s28, s28, 0x4000
	s_addc_u32 s29, s29, 0
	s_mov_b32 m0, s36
	ds_read_b128 v[180:183], v150 offset:32768
	ds_read_b128 v[184:187], v150 offset:33792
	ds_read_b128 v[188:191], v150 offset:34816
	ds_read_b128 v[192:195], v150 offset:35840
	ds_read_b128 v[196:199], v150 offset:36864
	ds_read_b128 v[200:203], v150 offset:37888
	ds_read_b128 v[204:207], v150 offset:38912
	ds_read_b128 v[208:211], v150 offset:39936
	global_load_lds_dwordx4 v136, s[28:29]
	s_mov_b32 m0, s37
	s_nop 0
	global_load_lds_dwordx4 v140, s[28:29]
	s_waitcnt vmcnt(8)
	s_waitcnt lgkmcnt(0)
	v_mfma_f32_16x16x32_bf16 v[132:135], v[52:55], v[180:183], v[132:135]
	v_mfma_f32_16x16x32_bf16 v[128:131], v[156:159], v[180:183], v[128:131]
	v_mfma_f32_16x16x32_bf16 v[124:127], v[52:55], v[188:191], v[124:127]
	v_mfma_f32_16x16x32_bf16 v[120:123], v[156:159], v[188:191], v[120:123]
	s_barrier
	v_mfma_f32_16x16x32_bf16 v[108:111], v[52:55], v[196:199], v[108:111]
	v_mfma_f32_16x16x32_bf16 v[104:107], v[156:159], v[196:199], v[104:107]
	v_mfma_f32_16x16x32_bf16 v[92:95], v[52:55], v[204:207], v[92:95]
	v_mfma_f32_16x16x32_bf16 v[88:91], v[156:159], v[204:207], v[88:91]
	v_mfma_f32_16x16x32_bf16 v[132:135], v[152:155], v[184:187], v[132:135]
	v_mfma_f32_16x16x32_bf16 v[128:131], v[160:163], v[184:187], v[128:131]
	v_mfma_f32_16x16x32_bf16 v[124:127], v[152:155], v[192:195], v[124:127]
	v_mfma_f32_16x16x32_bf16 v[120:123], v[160:163], v[192:195], v[120:123]
	v_mfma_f32_16x16x32_bf16 v[108:111], v[152:155], v[200:203], v[108:111]
	v_mfma_f32_16x16x32_bf16 v[104:107], v[160:163], v[200:203], v[104:107]
	v_mfma_f32_16x16x32_bf16 v[92:95], v[152:155], v[208:211], v[92:95]
	v_mfma_f32_16x16x32_bf16 v[88:91], v[160:163], v[208:211], v[88:91]
	v_mfma_f32_16x16x32_bf16 v[116:119], v[164:167], v[180:183], v[116:119]
	v_mfma_f32_16x16x32_bf16 v[112:115], v[172:175], v[180:183], v[112:115]
	v_mfma_f32_16x16x32_bf16 v[100:103], v[164:167], v[188:191], v[100:103]
	v_mfma_f32_16x16x32_bf16 v[96:99], v[172:175], v[188:191], v[96:99]
	v_mfma_f32_16x16x32_bf16 v[84:87], v[164:167], v[196:199], v[84:87]
	v_mfma_f32_16x16x32_bf16 v[80:83], v[172:175], v[196:199], v[80:83]
	v_mfma_f32_16x16x32_bf16 v[76:79], v[164:167], v[204:207], v[76:79]
	v_mfma_f32_16x16x32_bf16 v[72:75], v[172:175], v[204:207], v[72:75]
	v_mfma_f32_16x16x32_bf16 v[116:119], v[168:171], v[184:187], v[116:119]
	v_mfma_f32_16x16x32_bf16 v[112:115], v[176:179], v[184:187], v[112:115]
	v_mfma_f32_16x16x32_bf16 v[100:103], v[168:171], v[192:195], v[100:103]
	v_mfma_f32_16x16x32_bf16 v[96:99], v[176:179], v[192:195], v[96:99]
	v_mfma_f32_16x16x32_bf16 v[84:87], v[168:171], v[200:203], v[84:87]
	v_mfma_f32_16x16x32_bf16 v[80:83], v[176:179], v[200:203], v[80:83]
	v_mfma_f32_16x16x32_bf16 v[76:79], v[168:171], v[208:211], v[76:79]
	v_mfma_f32_16x16x32_bf16 v[72:75], v[176:179], v[208:211], v[72:75]
	s_barrier
; #define PG8_STAGE(bufoff, gbase, voff) do { _Pragma("unroll") for (int _i = 0; _i < 2; ++_i) \
;         __builtin_amdgcn_global_load_lds((const unsigned*)((const char*)(gbase) + (voff)[_i]), (PG8_LAS unsigned*)(lds + (bufoff) + ldsw + _i * 8192), 16, 0, 0); } while (0)
; #define PG8_LDA(dst, b, h) do { _Pragma("unroll") for (int m = 0; m < 4; ++m) _Pragma("unroll") for (int k = 0; k < 2; ++k) dst[m][k] = *(const PG8_LAS bf16x8*)(lds + PG8_SA(b, h) + aoff + m * 2048 + k * 1024); } while (0)
; #define PG8_MMA(ai, bj, At, Bt) do { __builtin_amdgcn_s_setprio(1); _Pragma("unroll") for (int m = 0; m < 4; ++m) _Pragma("unroll") for (int n = 0; n < 2; ++n) _Pragma("unroll") for (int k = 0; k < 2; ++k) \
;         acc[ai][bj][m][n] = __builtin_amdgcn_mfma_f32_16x16x32_bf16(Bt[n][k], At[m][k], acc[ai][bj][m][n], 0, 0, 0); __builtin_amdgcn_s_setprio(0); } while (0)
; #define PG8_WAIT_V(n) asm volatile("s_waitcnt vmcnt(" #n ")" ::: "memory")
; #define PG8_WAIT_L(n) asm volatile("s_waitcnt lgkmcnt(" #n ")" ::: "memory")
; #define PG8_BAR __builtin_amdgcn_s_barrier()
; #define PG8_SCHED __builtin_amdgcn_sched_barrier(0)
; template <class Epi, class Sched, bool ALIGN_EPI = false, bool SP2 = false, bool ABLK = false, bool BBLK = false>
; __device__ __forceinline__ void gemm_phase(PG8_LAS unsigned char* lds, const Gemm g, const Sched& S, const Epi& E) {
;     ...
;             PG8_LDA(At, 1, 1); PG8_STAGE(PG8_SB(1, 0), b3, voffB); PG8_STAGE(PG8_SB(1, 1), b3 + hstepB, voffB); PG8_STAGE(PG8_SA(1, 0), a3, voffA);
;             PG8_WAIT_V(8); PG8_WAIT_L(0); PG8_BAR; PG8_MMA(1, 0, At, B0); PG8_MMA(1, 1, At, B1); PG8_BAR; PG8_SCHED;
;     ...
;         if constexpr (ALIGN_EPI) { if (wr == 0) PG8_BAR; }
	s_add_u32 s28, s26, 0x8000
	s_addc_u32 s29, s27, 0
	s_add_i32 s68, s68, s34
	s_mov_b32 m0, s68
	ds_read_b128 v[180:183], v150 offset:49152
	ds_read_b128 v[184:187], v150 offset:50176
	ds_read_b128 v[188:191], v150 offset:51200
	ds_read_b128 v[192:195], v150 offset:52224
	ds_read_b128 v[196:199], v150 offset:53248
	ds_read_b128 v[200:203], v150 offset:54272
	ds_read_b128 v[204:207], v150 offset:55296
	ds_read_b128 v[208:211], v150 offset:56320
	global_load_lds_dwordx4 v138, s[28:29]
	s_add_i32 m0, s68, 0x2000
	s_add_u32 s26, s26, 0xc000
	s_addc_u32 s27, s27, 0
	global_load_lds_dwordx4 v142, s[28:29]
	s_add_i32 s28, s69, s34
	s_mov_b32 m0, s28
	s_nop 0
	global_load_lds_dwordx4 v138, s[26:27]
	s_add_i32 m0, s28, 0x2000
	s_nop 0
	global_load_lds_dwordx4 v142, s[26:27]
	s_mov_b32 m0, s64
	s_nop 0
	global_load_lds_dwordx4 v136, s[24:25]
	s_mov_b32 m0, s65
	s_nop 0
	global_load_lds_dwordx4 v140, s[24:25]
	s_waitcnt vmcnt(8)
	s_waitcnt lgkmcnt(0)
	v_mfma_f32_16x16x32_bf16 v[68:71], v[52:55], v[180:183], v[68:71]
	v_mfma_f32_16x16x32_bf16 v[64:67], v[156:159], v[180:183], v[64:67]
	v_mfma_f32_16x16x32_bf16 v[60:63], v[52:55], v[188:191], v[60:63]
	v_mfma_f32_16x16x32_bf16 v[56:59], v[156:159], v[188:191], v[56:59]
	s_barrier
	v_mfma_f32_16x16x32_bf16 v[44:47], v[52:55], v[196:199], v[44:47]
	v_mfma_f32_16x16x32_bf16 v[40:43], v[156:159], v[196:199], v[40:43]
	v_mfma_f32_16x16x32_bf16 v[24:27], v[52:55], v[204:207], v[24:27]
	v_mfma_f32_16x16x32_bf16 v[20:23], v[156:159], v[204:207], v[20:23]
	v_mfma_f32_16x16x32_bf16 v[68:71], v[152:155], v[184:187], v[68:71]
	v_mfma_f32_16x16x32_bf16 v[64:67], v[160:163], v[184:187], v[64:67]
	v_mfma_f32_16x16x32_bf16 v[60:63], v[152:155], v[192:195], v[60:63]
	v_mfma_f32_16x16x32_bf16 v[56:59], v[160:163], v[192:195], v[56:59]
	v_mfma_f32_16x16x32_bf16 v[44:47], v[152:155], v[200:203], v[44:47]
	v_mfma_f32_16x16x32_bf16 v[40:43], v[160:163], v[200:203], v[40:43]
	v_mfma_f32_16x16x32_bf16 v[24:27], v[152:155], v[208:211], v[24:27]
	v_mfma_f32_16x16x32_bf16 v[20:23], v[160:163], v[208:211], v[20:23]
	v_mfma_f32_16x16x32_bf16 v[36:39], v[164:167], v[180:183], v[36:39]
	v_mfma_f32_16x16x32_bf16 v[52:55], v[168:171], v[184:187], v[36:39]
	v_mfma_f32_16x16x32_bf16 v[36:39], v[172:175], v[180:183], v[48:51]
	v_mfma_f32_16x16x32_bf16 v[32:35], v[164:167], v[188:191], v[32:35]
	v_mfma_f32_16x16x32_bf16 v[28:31], v[172:175], v[188:191], v[28:31]
	v_mfma_f32_16x16x32_bf16 v[16:19], v[164:167], v[196:199], v[16:19]
	v_mfma_f32_16x16x32_bf16 v[12:15], v[172:175], v[196:199], v[12:15]
	v_mfma_f32_16x16x32_bf16 v[8:11], v[164:167], v[204:207], v[8:11]
	v_mfma_f32_16x16x32_bf16 v[4:7], v[172:175], v[204:207], v[4:7]
	v_mfma_f32_16x16x32_bf16 v[48:51], v[176:179], v[184:187], v[36:39]
	v_mfma_f32_16x16x32_bf16 v[32:35], v[168:171], v[192:195], v[32:35]
	v_mfma_f32_16x16x32_bf16 v[28:31], v[176:179], v[192:195], v[28:31]
	v_mfma_f32_16x16x32_bf16 v[16:19], v[168:171], v[200:203], v[16:19]
	v_mfma_f32_16x16x32_bf16 v[12:15], v[176:179], v[200:203], v[12:15]
	v_mfma_f32_16x16x32_bf16 v[8:11], v[168:171], v[208:211], v[8:11]
	v_mfma_f32_16x16x32_bf16 v[4:7], v[176:179], v[208:211], v[4:7]
	s_barrier
	s_add_i32 s13, s13, 2
	s_add_u32 s22, s22, 0x10000
	s_addc_u32 s23, s23, 0
	s_add_u32 s82, s82, 0x10000
	s_addc_u32 vcc_lo, vcc_lo, 0
	s_cmp_gt_u32 s13, 29
	s_cbranch_scc0 .LBB0_2111
	s_setprio 0
	s_and_b64 vcc, exec, s[6:7]
	s_movk_i32 s77, 0x1000
	s_cbranch_vccz .LBB0_2114
	s_barrier
